# prep phase dwordx4 stores flagged nt
# baseline (speedup 1.0000x reference)
; __device__ __forceinline__ unsigned cvt_pk_bf16(float lo, float hi) { unsigned r; asm volatile("v_cvt_pk_bf16_f32 %0, %1, %2" : "=v"(r) : "v"(lo), "v"(hi)); return r; }
; #define LAS __attribute__((address_space(3)))
; #define LDS_WAIT() asm volatile("s_waitcnt lgkmcnt(0)" ::: "memory")
; __device__ __forceinline__ void conv_item(const float* W, int ldw, int K, int c0, int k0, const float* gain, bf16_t* Wt, int n0, LAS float* scr, int lane) {
;     f32x4 v[16];
;     const int kr = lane >> 4, n4 = (lane & 15) * 4;
;     const float* src = W + (size_t)(k0 + kr) * ldw + c0 + n4;
; #pragma unroll
;     for (int i = 0; i < 16; ++i) v[i] = __builtin_nontemporal_load((const f32x4*)(src + (size_t)(4 * i) * ldw));
;     if (gain) {
; #pragma unroll
;         for (int i = 0; i < 16; ++i) v[i] = v[i] * gain[k0 + 4 * i + kr];
;     }
; #pragma unroll
;     for (int i = 0; i < 16; ++i) { const int k = 4 * i + kr; *(LAS f32x4*)(scr + k * 64 + (n4 ^ (((k >> 3) & 7) << 2))) = v[i]; }
;     LDS_WAIT(); asm volatile("" ::: "memory");
;     const int c = lane & 7;
; #pragma unroll
;     for (int j = 0; j < 8; ++j) { const int n = (lane >> 3) + 8 * j; const LAS float* s = scr + (8 * c) * 64 + (n ^ (c << 2));
;         u32x4 o; o.x = pg8::cvt_pk_bf16(s[0 * 64], s[1 * 64]); o.y = pg8::cvt_pk_bf16(s[2 * 64], s[3 * 64]); o.z = pg8::cvt_pk_bf16(s[4 * 64], s[5 * 64]); o.w = pg8::cvt_pk_bf16(s[6 * 64], s[7 * 64]);
;         *(u32x4*)(Wt + (size_t)(n0 + n) * K + k0 + 8 * c) = o; }
.LBB0_178:
	s_ashr_i32 s2, s15, 31
	s_lshr_b32 s2, s2, 28
	s_add_i32 s2, s15, s2
	s_ashr_i32 s3, s2, 4
	s_lshl_b32 s12, s3, 6
	v_or_b32_e32 v6, s12, v74
	s_lshl_b32 s2, s3, 10
	v_ashrrev_i32_e32 v7, 31, v6
	s_sub_i32 s2, s5, s2
	v_lshlrev_b64 v[6:7], 12, v[6:7]
	v_lshl_add_u64 v[6:7], s[0:1], 0, v[6:7]
	s_ashr_i32 s3, s2, 31
	v_lshl_add_u64 v[6:7], s[2:3], 2, v[6:7]
	v_lshlrev_b32_e32 v208, 2, v0
	v_lshl_add_u64 v[112:113], v[6:7], 0, v[208:209]
	v_add_co_u32_e32 v44, vcc, s17, v112
	global_load_dwordx4 v[6:9], v[112:113], off nt
	s_nop 0
	v_addc_co_u32_e32 v45, vcc, 0, v113, vcc
	v_add_co_u32_e32 v48, vcc, s18, v112
	global_load_dwordx4 v[44:47], v[44:45], off nt
	s_nop 0
	v_addc_co_u32_e32 v49, vcc, 0, v113, vcc
	v_add_co_u32_e32 v52, vcc, s19, v112
	global_load_dwordx4 v[48:51], v[48:49], off nt
	s_nop 0
	v_addc_co_u32_e32 v53, vcc, 0, v113, vcc
	v_add_co_u32_e32 v56, vcc, s20, v112
	global_load_dwordx4 v[52:55], v[52:53], off nt
	s_nop 0
	v_addc_co_u32_e32 v57, vcc, 0, v113, vcc
	v_add_co_u32_e32 v60, vcc, s21, v112
	global_load_dwordx4 v[56:59], v[56:57], off nt
	s_nop 0
	v_addc_co_u32_e32 v61, vcc, 0, v113, vcc
	v_add_co_u32_e32 v66, vcc, s26, v112
	global_load_dwordx4 v[60:63], v[60:61], off nt
	s_nop 0
	v_addc_co_u32_e32 v67, vcc, 0, v113, vcc
	v_add_co_u32_e32 v70, vcc, s27, v112
	global_load_dwordx4 v[66:69], v[66:67], off nt
	s_nop 0
	v_addc_co_u32_e32 v71, vcc, 0, v113, vcc
	v_add_co_u32_e32 v84, vcc, s28, v112
	global_load_dwordx4 v[70:73], v[70:71], off nt
	s_nop 0
	v_addc_co_u32_e32 v85, vcc, 0, v113, vcc
	v_add_co_u32_e32 v88, vcc, s29, v112
	global_load_dwordx4 v[84:87], v[84:85], off nt
	s_nop 0
	v_addc_co_u32_e32 v89, vcc, 0, v113, vcc
	v_add_co_u32_e32 v92, vcc, s30, v112
	global_load_dwordx4 v[88:91], v[88:89], off nt
	s_nop 0
	v_addc_co_u32_e32 v93, vcc, 0, v113, vcc
	v_add_co_u32_e32 v96, vcc, s31, v112
	global_load_dwordx4 v[92:95], v[92:93], off nt
	s_nop 0
	v_addc_co_u32_e32 v97, vcc, 0, v113, vcc
	v_add_co_u32_e32 v100, vcc, s36, v112
	global_load_dwordx4 v[96:99], v[96:97], off nt
	s_nop 0
	v_addc_co_u32_e32 v101, vcc, 0, v113, vcc
	v_add_co_u32_e32 v104, vcc, s37, v112
	global_load_dwordx4 v[100:103], v[100:101], off nt
	s_nop 0
	v_addc_co_u32_e32 v105, vcc, 0, v113, vcc
	v_add_co_u32_e32 v108, vcc, s38, v112
	global_load_dwordx4 v[104:107], v[104:105], off nt
	s_nop 0
	v_addc_co_u32_e32 v109, vcc, 0, v113, vcc
	v_add_co_u32_e32 v112, vcc, s39, v112
	global_load_dwordx4 v[108:111], v[108:109], off nt
	s_nop 0
	v_addc_co_u32_e32 v113, vcc, 0, v113, vcc
	global_load_dwordx4 v[112:115], v[112:113], off nt
	s_ashr_i32 s13, s12, 31
	s_add_i32 s15, s15, s16
	s_add_i32 s5, s5, s14
	s_cmpk_lt_i32 s15, 0x100
	s_waitcnt vmcnt(0)
	ds_write_b128 v27, v[6:9]
	s_waitcnt vmcnt(14)
	ds_write_b128 v27, v[44:47] offset:1024
	s_waitcnt vmcnt(13)
	ds_write_b128 v28, v[48:51] offset:2048
	s_waitcnt vmcnt(12)
	ds_write_b128 v28, v[52:55] offset:3072
	s_waitcnt vmcnt(11)
	ds_write_b128 v29, v[56:59] offset:4096
	s_waitcnt vmcnt(10)
	ds_write_b128 v29, v[60:63] offset:5120
	s_waitcnt vmcnt(9)
	ds_write_b128 v30, v[66:69] offset:6144
	s_waitcnt vmcnt(8)
	ds_write_b128 v30, v[70:73] offset:7168
	s_waitcnt vmcnt(7)
	ds_write_b128 v31, v[84:87] offset:8192
	s_waitcnt vmcnt(6)
	ds_write_b128 v31, v[88:91] offset:9216
	s_waitcnt vmcnt(5)
	ds_write_b128 v32, v[92:95] offset:10240
	s_waitcnt vmcnt(4)
	ds_write_b128 v32, v[96:99] offset:11264
	s_waitcnt vmcnt(3)
	ds_write_b128 v33, v[100:103] offset:12288
	s_waitcnt vmcnt(2)
	ds_write_b128 v33, v[104:107] offset:13312
	s_waitcnt vmcnt(1)
	ds_write_b128 v34, v[108:111] offset:14336
	s_waitcnt vmcnt(0)
	ds_write_b128 v34, v[112:115] offset:15360
	s_waitcnt lgkmcnt(0)
	ds_read2st64_b32 v[8:9], v35 offset1:1
	s_waitcnt lgkmcnt(0)
	v_cvt_pk_bf16_f32 v44, v8, v9
	ds_read2st64_b32 v[8:9], v35 offset0:2 offset1:3
	s_waitcnt lgkmcnt(0)
	v_cvt_pk_bf16_f32 v45, v8, v9
	ds_read2st64_b32 v[8:9], v35 offset0:4 offset1:5
	s_waitcnt lgkmcnt(0)
	v_cvt_pk_bf16_f32 v46, v8, v9
	ds_read2st64_b32 v[8:9], v35 offset0:6 offset1:7
	s_waitcnt lgkmcnt(0)
	v_cvt_pk_bf16_f32 v47, v8, v9
	v_add_u32_e32 v8, s2, v75
	v_ashrrev_i32_e32 v9, 31, v8
	v_lshl_add_u64 v[6:7], s[12:13], 1, v[4:5]
	v_lshlrev_b64 v[48:49], 11, v[8:9]
	v_lshl_add_u64 v[48:49], v[6:7], 0, v[48:49]
	global_store_dwordx4 v[48:49], v[44:47], off nt
	ds_read2st64_b32 v[44:45], v36 offset1:1
	s_waitcnt lgkmcnt(0)
; __device__ __forceinline__ unsigned cvt_pk_bf16(float lo, float hi) { unsigned r; asm volatile("v_cvt_pk_bf16_f32 %0, %1, %2" : "=v"(r) : "v"(lo), "v"(hi)); return r; }
; #define LAS __attribute__((address_space(3)))
; #define LDS_WAIT() asm volatile("s_waitcnt lgkmcnt(0)" ::: "memory")
; __device__ __forceinline__ void conv_item(const float* W, int ldw, int K, int c0, int k0, const float* gain, bf16_t* Wt, int n0, LAS float* scr, int lane) {
;     ...
;     const int c = lane & 7;
; #pragma unroll
;     for (int j = 0; j < 8; ++j) { const int n = (lane >> 3) + 8 * j; const LAS float* s = scr + (8 * c) * 64 + (n ^ (c << 2));
;         u32x4 o; o.x = pg8::cvt_pk_bf16(s[0 * 64], s[1 * 64]); o.y = pg8::cvt_pk_bf16(s[2 * 64], s[3 * 64]); o.z = pg8::cvt_pk_bf16(s[4 * 64], s[5 * 64]); o.w = pg8::cvt_pk_bf16(s[6 * 64], s[7 * 64]);
;         *(u32x4*)(Wt + (size_t)(n0 + n) * K + k0 + 8 * c) = o; }
;     LDS_WAIT(); asm volatile("" ::: "memory");
	v_cvt_pk_bf16_f32 v44, v44, v45
	ds_read2st64_b32 v[46:47], v36 offset0:2 offset1:3
	s_waitcnt lgkmcnt(0)
	v_cvt_pk_bf16_f32 v45, v46, v47
	ds_read2st64_b32 v[46:47], v36 offset0:4 offset1:5
	s_waitcnt lgkmcnt(0)
	v_cvt_pk_bf16_f32 v46, v46, v47
	ds_read2st64_b32 v[48:49], v36 offset0:6 offset1:7
	s_waitcnt lgkmcnt(0)
	v_cvt_pk_bf16_f32 v47, v48, v49
	v_add_u32_e32 v48, 8, v8
	v_ashrrev_i32_e32 v49, 31, v48
	v_lshlrev_b64 v[48:49], 11, v[48:49]
	v_lshl_add_u64 v[48:49], v[6:7], 0, v[48:49]
	global_store_dwordx4 v[48:49], v[44:47], off nt
	ds_read2st64_b32 v[44:45], v37 offset1:1
	s_waitcnt lgkmcnt(0)
	v_cvt_pk_bf16_f32 v44, v44, v45
	ds_read2st64_b32 v[46:47], v37 offset0:2 offset1:3
	s_waitcnt lgkmcnt(0)
	v_cvt_pk_bf16_f32 v45, v46, v47
	ds_read2st64_b32 v[46:47], v37 offset0:4 offset1:5
	s_waitcnt lgkmcnt(0)
	v_cvt_pk_bf16_f32 v46, v46, v47
	ds_read2st64_b32 v[48:49], v37 offset0:6 offset1:7
	s_waitcnt lgkmcnt(0)
	v_cvt_pk_bf16_f32 v47, v48, v49
	v_add_u32_e32 v48, 16, v8
	v_ashrrev_i32_e32 v49, 31, v48
	v_lshlrev_b64 v[48:49], 11, v[48:49]
	v_lshl_add_u64 v[48:49], v[6:7], 0, v[48:49]
	global_store_dwordx4 v[48:49], v[44:47], off nt
	ds_read2st64_b32 v[44:45], v38 offset1:1
	s_waitcnt lgkmcnt(0)
	v_cvt_pk_bf16_f32 v44, v44, v45
	ds_read2st64_b32 v[46:47], v38 offset0:2 offset1:3
	s_waitcnt lgkmcnt(0)
	v_cvt_pk_bf16_f32 v45, v46, v47
	ds_read2st64_b32 v[46:47], v38 offset0:4 offset1:5
	s_waitcnt lgkmcnt(0)
	v_cvt_pk_bf16_f32 v46, v46, v47
	ds_read2st64_b32 v[48:49], v38 offset0:6 offset1:7
	s_waitcnt lgkmcnt(0)
	v_cvt_pk_bf16_f32 v47, v48, v49
	v_add_u32_e32 v48, 24, v8
	v_ashrrev_i32_e32 v49, 31, v48
	v_lshlrev_b64 v[48:49], 11, v[48:49]
	v_lshl_add_u64 v[48:49], v[6:7], 0, v[48:49]
	global_store_dwordx4 v[48:49], v[44:47], off nt
	ds_read2st64_b32 v[44:45], v39 offset1:1
	s_waitcnt lgkmcnt(0)
	v_cvt_pk_bf16_f32 v44, v44, v45
	ds_read2st64_b32 v[46:47], v39 offset0:2 offset1:3
	s_waitcnt lgkmcnt(0)
	v_cvt_pk_bf16_f32 v45, v46, v47
	ds_read2st64_b32 v[46:47], v39 offset0:4 offset1:5
	s_waitcnt lgkmcnt(0)
	v_cvt_pk_bf16_f32 v46, v46, v47
	ds_read2st64_b32 v[48:49], v39 offset0:6 offset1:7
	s_waitcnt lgkmcnt(0)
	v_cvt_pk_bf16_f32 v47, v48, v49
	v_add_u32_e32 v48, 32, v8
	v_ashrrev_i32_e32 v49, 31, v48
	v_lshlrev_b64 v[48:49], 11, v[48:49]
	v_lshl_add_u64 v[48:49], v[6:7], 0, v[48:49]
	global_store_dwordx4 v[48:49], v[44:47], off nt
	ds_read2st64_b32 v[44:45], v40 offset1:1
	s_waitcnt lgkmcnt(0)
	v_cvt_pk_bf16_f32 v44, v44, v45
	ds_read2st64_b32 v[46:47], v40 offset0:2 offset1:3
	s_waitcnt lgkmcnt(0)
	v_cvt_pk_bf16_f32 v45, v46, v47
	ds_read2st64_b32 v[46:47], v40 offset0:4 offset1:5
	s_waitcnt lgkmcnt(0)
	v_cvt_pk_bf16_f32 v46, v46, v47
	ds_read2st64_b32 v[48:49], v40 offset0:6 offset1:7
	s_waitcnt lgkmcnt(0)
	v_cvt_pk_bf16_f32 v47, v48, v49
	v_add_u32_e32 v48, 40, v8
	v_ashrrev_i32_e32 v49, 31, v48
	v_lshlrev_b64 v[48:49], 11, v[48:49]
	v_lshl_add_u64 v[48:49], v[6:7], 0, v[48:49]
	global_store_dwordx4 v[48:49], v[44:47], off nt
	ds_read2st64_b32 v[44:45], v41 offset1:1
	s_waitcnt lgkmcnt(0)
	v_cvt_pk_bf16_f32 v44, v44, v45
	ds_read2st64_b32 v[46:47], v41 offset0:2 offset1:3
	s_waitcnt lgkmcnt(0)
	v_cvt_pk_bf16_f32 v45, v46, v47
	ds_read2st64_b32 v[46:47], v41 offset0:4 offset1:5
	s_waitcnt lgkmcnt(0)
	v_cvt_pk_bf16_f32 v46, v46, v47
	ds_read2st64_b32 v[48:49], v41 offset0:6 offset1:7
	s_waitcnt lgkmcnt(0)
	v_cvt_pk_bf16_f32 v47, v48, v49
	v_add_u32_e32 v48, 48, v8
	v_ashrrev_i32_e32 v49, 31, v48
	v_lshlrev_b64 v[48:49], 11, v[48:49]
	v_lshl_add_u64 v[48:49], v[6:7], 0, v[48:49]
	v_add_u32_e32 v8, 56, v8
	global_store_dwordx4 v[48:49], v[44:47], off nt
	ds_read2st64_b32 v[44:45], v42 offset1:1
	v_ashrrev_i32_e32 v9, 31, v8
	s_waitcnt lgkmcnt(0)
	v_cvt_pk_bf16_f32 v44, v44, v45
	ds_read2st64_b32 v[46:47], v42 offset0:2 offset1:3
	v_lshlrev_b64 v[8:9], 11, v[8:9]
	s_waitcnt lgkmcnt(0)
	v_cvt_pk_bf16_f32 v45, v46, v47
	ds_read2st64_b32 v[46:47], v42 offset0:4 offset1:5
	v_lshl_add_u64 v[6:7], v[6:7], 0, v[8:9]
	s_waitcnt lgkmcnt(0)
	v_cvt_pk_bf16_f32 v46, v46, v47
	ds_read2st64_b32 v[48:49], v42 offset0:6 offset1:7
	s_waitcnt lgkmcnt(0)
	v_cvt_pk_bf16_f32 v47, v48, v49
	global_store_dwordx4 v[6:7], v[44:47], off nt
	s_waitcnt lgkmcnt(0)
	s_cbranch_scc1 .LBB0_178
	s_mov_b32 s66, 0x1c000
	s_mov_b32 s65, 0xc000
	v_mov_b64_e32 v[66:67], v[0:1]

; __device__ __forceinline__ unsigned cvt_pk_bf16(float lo, float hi) { unsigned r; asm volatile("v_cvt_pk_bf16_f32 %0, %1, %2" : "=v"(r) : "v"(lo), "v"(hi)); return r; }
; #define LAS __attribute__((address_space(3)))
; #define LDS_WAIT() asm volatile("s_waitcnt lgkmcnt(0)" ::: "memory")
; __device__ __forceinline__ void conv_item(const float* W, int ldw, int K, int c0, int k0, const float* gain, bf16_t* Wt, int n0, LAS float* scr, int lane) {
;     ...
;     for (int i = 0; i < 16; ++i) { const int k = 4 * i + kr; *(LAS f32x4*)(scr + k * 64 + (n4 ^ (((k >> 3) & 7) << 2))) = v[i]; }
;     LDS_WAIT(); asm volatile("" ::: "memory");
;     const int c = lane & 7;
; #pragma unroll
;     for (int j = 0; j < 8; ++j) { const int n = (lane >> 3) + 8 * j; const LAS float* s = scr + (8 * c) * 64 + (n ^ (c << 2));
;         u32x4 o; o.x = pg8::cvt_pk_bf16(s[0 * 64], s[1 * 64]); o.y = pg8::cvt_pk_bf16(s[2 * 64], s[3 * 64]); o.z = pg8::cvt_pk_bf16(s[4 * 64], s[5 * 64]); o.w = pg8::cvt_pk_bf16(s[6 * 64], s[7 * 64]);
;         *(u32x4*)(Wt + (size_t)(n0 + n) * K + k0 + 8 * c) = o; }
;     LDS_WAIT(); asm volatile("" ::: "memory");
.LBB0_184:
	s_waitcnt vmcnt(0)
	ds_write_b128 v83, v[0:3]
	s_waitcnt vmcnt(14)
	ds_write_b128 v83, v[4:7] offset:1024
	s_waitcnt vmcnt(13)
	ds_write_b128 v84, v[8:11] offset:2048
	s_waitcnt vmcnt(12)
	ds_write_b128 v84, v[12:15] offset:3072
	s_waitcnt vmcnt(11)
	ds_write_b128 v85, v[16:19] offset:4096
	s_waitcnt vmcnt(10)
	ds_write_b128 v85, v[20:23] offset:5120
	s_waitcnt vmcnt(9)
	ds_write_b128 v86, v[24:27] offset:6144
	s_waitcnt vmcnt(8)
	ds_write_b128 v86, v[28:31] offset:7168
	s_waitcnt vmcnt(7)
	ds_write_b128 v87, v[32:35] offset:8192
	s_waitcnt vmcnt(6)
	ds_write_b128 v87, v[36:39] offset:9216
	s_waitcnt vmcnt(5)
	ds_write_b128 v88, v[40:43] offset:10240
	s_waitcnt vmcnt(4)
	ds_write_b128 v88, v[44:47] offset:11264
	s_waitcnt vmcnt(3)
	ds_write_b128 v89, v[48:51] offset:12288
	s_waitcnt vmcnt(2)
	ds_write_b128 v89, v[52:55] offset:13312
	s_waitcnt vmcnt(1)
	ds_write_b128 v90, v[56:59] offset:14336
	s_waitcnt vmcnt(0)
	ds_write_b128 v90, v[60:63] offset:15360
	s_waitcnt lgkmcnt(0)
	ds_read2st64_b32 v[0:1], v91 offset1:1
	s_waitcnt lgkmcnt(0)
	v_cvt_pk_bf16_f32 v0, v0, v1
	ds_read2st64_b32 v[2:3], v91 offset0:2 offset1:3
	s_waitcnt lgkmcnt(0)
	v_cvt_pk_bf16_f32 v1, v2, v3
	ds_read2st64_b32 v[2:3], v91 offset0:4 offset1:5
	s_waitcnt lgkmcnt(0)
	v_cvt_pk_bf16_f32 v2, v2, v3
	ds_read2st64_b32 v[4:5], v91 offset0:6 offset1:7
	s_waitcnt lgkmcnt(0)
	v_cvt_pk_bf16_f32 v3, v4, v5
	v_add_u32_e32 v4, s21, v75
	s_ashr_i32 s17, s16, 31
	v_ashrrev_i32_e32 v5, 31, v4
	v_lshl_add_u64 v[6:7], s[16:17], 1, v[70:71]
	v_lshlrev_b64 v[4:5], 11, v[4:5]
	ds_read2st64_b32 v[8:9], v92 offset1:1
	v_lshl_add_u64 v[4:5], v[6:7], 0, v[4:5]
	global_store_dwordx4 v[4:5], v[0:3], off nt
	v_readlane_b32 s16, v254, 22
	s_add_i32 s5, s5, s16
	s_waitcnt lgkmcnt(0)
	v_cvt_pk_bf16_f32 v0, v8, v9
	v_add_u32_e32 v8, s21, v76
	v_ashrrev_i32_e32 v9, 31, v8
	ds_read2st64_b32 v[2:3], v92 offset0:2 offset1:3
	v_lshlrev_b64 v[8:9], 11, v[8:9]
	s_waitcnt lgkmcnt(0)
	v_cvt_pk_bf16_f32 v1, v2, v3
	ds_read2st64_b32 v[2:3], v92 offset0:4 offset1:5
	v_lshl_add_u64 v[8:9], v[6:7], 0, v[8:9]
	s_waitcnt lgkmcnt(0)
	v_cvt_pk_bf16_f32 v2, v2, v3
	ds_read2st64_b32 v[4:5], v92 offset0:6 offset1:7
	s_waitcnt lgkmcnt(0)
	v_cvt_pk_bf16_f32 v3, v4, v5
	global_store_dwordx4 v[8:9], v[0:3], off nt
	v_add_u32_e32 v8, s21, v77
	v_ashrrev_i32_e32 v9, 31, v8
	ds_read2st64_b32 v[4:5], v93 offset1:1
	s_waitcnt lgkmcnt(0)
	v_cvt_pk_bf16_f32 v0, v4, v5
	ds_read2st64_b32 v[2:3], v93 offset0:2 offset1:3
	v_lshlrev_b64 v[8:9], 11, v[8:9]
	s_waitcnt lgkmcnt(0)
	v_cvt_pk_bf16_f32 v1, v2, v3
	ds_read2st64_b32 v[2:3], v93 offset0:4 offset1:5
	v_lshl_add_u64 v[8:9], v[6:7], 0, v[8:9]
	s_waitcnt lgkmcnt(0)
	v_cvt_pk_bf16_f32 v2, v2, v3
	ds_read2st64_b32 v[4:5], v93 offset0:6 offset1:7
	s_waitcnt lgkmcnt(0)
	v_cvt_pk_bf16_f32 v3, v4, v5
	global_store_dwordx4 v[8:9], v[0:3], off nt
	v_add_u32_e32 v8, s21, v78
	v_ashrrev_i32_e32 v9, 31, v8
	ds_read2st64_b32 v[4:5], v94 offset1:1
	s_waitcnt lgkmcnt(0)
	v_cvt_pk_bf16_f32 v0, v4, v5
	ds_read2st64_b32 v[2:3], v94 offset0:2 offset1:3
	v_lshlrev_b64 v[8:9], 11, v[8:9]
	s_waitcnt lgkmcnt(0)
	v_cvt_pk_bf16_f32 v1, v2, v3
	ds_read2st64_b32 v[2:3], v94 offset0:4 offset1:5
	v_lshl_add_u64 v[8:9], v[6:7], 0, v[8:9]
	s_waitcnt lgkmcnt(0)
	v_cvt_pk_bf16_f32 v2, v2, v3
	ds_read2st64_b32 v[4:5], v94 offset0:6 offset1:7
	s_waitcnt lgkmcnt(0)
	v_cvt_pk_bf16_f32 v3, v4, v5
	global_store_dwordx4 v[8:9], v[0:3], off nt
	v_add_u32_e32 v8, s21, v79
	v_ashrrev_i32_e32 v9, 31, v8
	ds_read2st64_b32 v[4:5], v95 offset1:1
	s_waitcnt lgkmcnt(0)
	v_cvt_pk_bf16_f32 v0, v4, v5
	ds_read2st64_b32 v[2:3], v95 offset0:2 offset1:3
	v_lshlrev_b64 v[8:9], 11, v[8:9]
	s_waitcnt lgkmcnt(0)
	v_cvt_pk_bf16_f32 v1, v2, v3
	ds_read2st64_b32 v[2:3], v95 offset0:4 offset1:5
	v_lshl_add_u64 v[8:9], v[6:7], 0, v[8:9]
	s_waitcnt lgkmcnt(0)
	v_cvt_pk_bf16_f32 v2, v2, v3
	ds_read2st64_b32 v[4:5], v95 offset0:6 offset1:7
	s_waitcnt lgkmcnt(0)
	v_cvt_pk_bf16_f32 v3, v4, v5
	global_store_dwordx4 v[8:9], v[0:3], off nt
	v_add_u32_e32 v8, s21, v80
	ds_read2st64_b32 v[4:5], v96 offset1:1
	s_waitcnt lgkmcnt(0)
	v_cvt_pk_bf16_f32 v0, v4, v5
	ds_read2st64_b32 v[2:3], v96 offset0:2 offset1:3
	v_ashrrev_i32_e32 v9, 31, v8
	s_waitcnt lgkmcnt(0)
	v_cvt_pk_bf16_f32 v1, v2, v3
	ds_read2st64_b32 v[2:3], v96 offset0:4 offset1:5
	v_lshlrev_b64 v[8:9], 11, v[8:9]
	s_waitcnt lgkmcnt(0)
	v_cvt_pk_bf16_f32 v2, v2, v3
	ds_read2st64_b32 v[4:5], v96 offset0:6 offset1:7
	s_waitcnt lgkmcnt(0)
	v_cvt_pk_bf16_f32 v3, v4, v5
	v_lshl_add_u64 v[8:9], v[6:7], 0, v[8:9]
	ds_read2st64_b32 v[4:5], v97 offset1:1
	global_store_dwordx4 v[8:9], v[0:3], off nt
	v_add_u32_e32 v8, s21, v81
	v_ashrrev_i32_e32 v9, 31, v8
	s_waitcnt lgkmcnt(0)
	v_cvt_pk_bf16_f32 v0, v4, v5
	ds_read2st64_b32 v[2:3], v97 offset0:2 offset1:3
	s_waitcnt lgkmcnt(0)
	v_cvt_pk_bf16_f32 v1, v2, v3
	ds_read2st64_b32 v[2:3], v97 offset0:4 offset1:5
	s_waitcnt lgkmcnt(0)
	v_cvt_pk_bf16_f32 v2, v2, v3
	ds_read2st64_b32 v[4:5], v97 offset0:6 offset1:7
	v_lshlrev_b64 v[8:9], 11, v[8:9]
	s_waitcnt lgkmcnt(0)
	v_cvt_pk_bf16_f32 v3, v4, v5
	ds_read2st64_b32 v[4:5], v98 offset1:1
	v_lshl_add_u64 v[8:9], v[6:7], 0, v[8:9]
	global_store_dwordx4 v[8:9], v[0:3], off nt
	s_add_i32 s18, s18, s19
	s_cmpk_lt_i32 s5, 0x300
	s_waitcnt lgkmcnt(0)
	v_cvt_pk_bf16_f32 v0, v4, v5
	v_add_u32_e32 v4, s21, v82
	v_ashrrev_i32_e32 v5, 31, v4
	ds_read2st64_b32 v[2:3], v98 offset0:2 offset1:3
	v_lshlrev_b64 v[4:5], 11, v[4:5]
	s_waitcnt lgkmcnt(0)
	v_cvt_pk_bf16_f32 v1, v2, v3
	ds_read2st64_b32 v[2:3], v98 offset0:4 offset1:5
	v_lshl_add_u64 v[4:5], v[6:7], 0, v[4:5]
	s_waitcnt lgkmcnt(0)
	v_cvt_pk_bf16_f32 v2, v2, v3
	ds_read2st64_b32 v[8:9], v98 offset0:6 offset1:7
	s_waitcnt lgkmcnt(0)
	v_cvt_pk_bf16_f32 v3, v8, v9
	global_store_dwordx4 v[4:5], v[0:3], off nt
	s_waitcnt lgkmcnt(0)
	v_readlane_b32 s17, v254, 23
	s_cbranch_scc0 .LBB0_181

; __device__ __forceinline__ unsigned pk2(float lo, float hi) { return f2bf(lo) | (f2bf(hi) << 16); }
; __device__ __forceinline__ void s5_gen(LAS unsigned char* lds, const S5In P, int g, int q, bf16_t* Bst, bf16_t* Bout, const int tid) {
;     ...
;     { const int di = q >> 1, ri = q & 1;
;       for (int cid = tid; cid < 2048; cid += 512) { const int nl = cid >> 5, k0 = (cid & 31) * 8, r = k0 >> 4, ch0 = k0 & 15;
;         const f32x2v w = pw[(di * 64 + nl) * 17 + (di == 0 ? 15 - r : r)]; float v[8];
; #pragma unroll
;         for (int j = 0; j < 8; ++j) { const f32x2v b = bb[(di * 64 + nl) * 16 + ch0 + j]; const float zr = w.x * b.x - w.y * b.y, zi = w.x * b.y + w.y * b.x; v[j] = (ri == 0 ? zr : zi) * P.gain[g * 16 + ch0 + j]; }
;         u32x4 o; o.x = pk2(v[0], v[1]); o.y = pk2(v[2], v[3]); o.z = pk2(v[4], v[5]); o.w = pk2(v[6], v[7]);
;         *(u32x4*)(Bst + ((size_t)g * 256 + q * 64 + nl) * 256 + k0) = o; } }
.LBB0_201:
	v_ashrrev_i32_e32 v2, 5, v1
	v_bfe_u32 v6, v0, 4, 4
	v_and_b32_e32 v3, 8, v0
	v_and_b32_e32 v5, 0xf8, v0
	v_add_u32_e32 v7, 0x200, v1
	v_add_u32_e32 v8, s49, v2
	v_xor_b32_e32 v9, 15, v6
	v_or_b32_e32 v4, s50, v3
	v_cmp_lt_i32_e64 s[44:45], s51, v1
	v_lshlrev_b32_e32 v10, 3, v3
	v_ashrrev_i32_e32 v3, 31, v2
	v_lshlrev_b32_e32 v208, 1, v5
	v_mov_b32_e32 v1, v7
	v_cndmask_b32_e32 v6, v6, v9, vcc
	v_lshlrev_b32_e32 v7, 7, v8
	v_ashrrev_i32_e32 v5, 31, v4
	v_lshl_add_u64 v[2:3], s[30:31], 0, v[2:3]
	v_lshlrev_b32_e32 v12, 3, v6
	v_add3_u32 v24, 0, v7, v10
	v_lshl_add_u64 v[6:7], v[4:5], 2, s[96:97]
	v_mul_lo_u32 v11, v8, s17
	v_lshlrev_b64 v[22:23], 9, v[2:3]
	global_load_dwordx4 v[2:5], v[6:7], off
	s_nop 0
	global_load_dwordx4 v[6:9], v[6:7], off offset:16
	v_add3_u32 v25, 0, v11, v12
	ds_read_b128 v[10:13], v24 offset:17424
	ds_read_b128 v[14:17], v24 offset:17440
	ds_read_b128 v[18:21], v24 offset:17456
	v_lshl_add_u64 v[26:27], s[18:19], 0, v[22:23]
	ds_read_b64 v[28:29], v25
	ds_read_b128 v[22:25], v24 offset:17408
	s_waitcnt lgkmcnt(0)
	v_mov_b32_e32 v31, v10
	v_mov_b32_e32 v33, v11
	v_mov_b32_e32 v45, v11
	s_waitcnt lgkmcnt(3)
	v_mov_b32_e32 v52, v14
	s_waitcnt lgkmcnt(2)
	v_mov_b32_e32 v53, v18
	v_mov_b32_e32 v54, v15
	v_mov_b32_e32 v55, v19
	v_mov_b32_e32 v56, v14
	v_pk_mov_b32 v[14:15], v[14:15], v[18:19] op_sel:[1,0]
	v_mov_b32_e32 v18, v16
	v_mov_b32_e32 v58, v17
	v_mov_b32_e32 v59, v21
	v_mov_b32_e32 v60, v16
	v_pk_mov_b32 v[16:17], v[16:17], v[20:21] op_sel:[1,0]
	s_waitcnt lgkmcnt(0)
	v_mov_b32_e32 v32, v23
	v_pk_mov_b32 v[10:11], v[22:23], v[10:11] op_sel:[1,0]
	v_mov_b32_e32 v47, v12
	v_mov_b32_e32 v49, v13
	v_mov_b32_e32 v51, v13
	v_mov_b32_e32 v57, v19
	v_mov_b32_e32 v19, v20
	v_mov_b32_e32 v61, v21
	v_mov_b32_e32 v30, v22
	v_mov_b32_e32 v44, v22
	v_mov_b32_e32 v46, v24
	v_mov_b32_e32 v48, v25
	v_mov_b32_e32 v50, v24
	v_pk_mov_b32 v[12:13], v[24:25], v[12:13] op_sel:[1,0]
	v_pk_mul_f32 v[20:21], v[28:29], v[54:55] op_sel:[1,0]
	v_pk_mul_f32 v[14:15], v[28:29], v[14:15]
	v_pk_mul_f32 v[22:23], v[28:29], v[58:59] op_sel:[1,0]
	v_pk_mul_f32 v[16:17], v[28:29], v[16:17]
	v_pk_mul_f32 v[24:25], v[28:29], v[32:33] op_sel:[1,0]
	v_pk_mul_f32 v[10:11], v[28:29], v[10:11]
	v_pk_mul_f32 v[32:33], v[28:29], v[48:49] op_sel:[1,0]
	v_pk_mul_f32 v[12:13], v[28:29], v[12:13]
	v_pk_fma_f32 v[20:21], v[28:29], v[52:53], v[20:21] op_sel_hi:[0,1,1] neg_lo:[0,0,1] neg_hi:[0,0,1]
	v_pk_fma_f32 v[14:15], v[28:29], v[56:57], v[14:15] op_sel:[1,0,0] op_sel_hi:[0,1,1]
	v_pk_fma_f32 v[18:19], v[28:29], v[18:19], v[22:23] op_sel_hi:[0,1,1] neg_lo:[0,0,1] neg_hi:[0,0,1]
	v_pk_fma_f32 v[16:17], v[28:29], v[60:61], v[16:17] op_sel:[1,0,0] op_sel_hi:[0,1,1]
	v_pk_fma_f32 v[22:23], v[28:29], v[30:31], v[24:25] op_sel_hi:[0,1,1] neg_lo:[0,0,1] neg_hi:[0,0,1]
	v_pk_fma_f32 v[10:11], v[28:29], v[44:45], v[10:11] op_sel:[1,0,0] op_sel_hi:[0,1,1]
	v_pk_fma_f32 v[24:25], v[28:29], v[46:47], v[32:33] op_sel_hi:[0,1,1] neg_lo:[0,0,1] neg_hi:[0,0,1]
	v_pk_fma_f32 v[12:13], v[28:29], v[50:51], v[12:13] op_sel:[1,0,0] op_sel_hi:[0,1,1]
	v_cndmask_b32_e64 v15, v15, v21, s[42:43]
	v_cndmask_b32_e64 v14, v14, v20, s[42:43]
	v_cndmask_b32_e64 v17, v17, v19, s[42:43]
	v_cndmask_b32_e64 v16, v16, v18, s[42:43]
	v_cndmask_b32_e64 v11, v11, v23, s[42:43]
	v_cndmask_b32_e64 v10, v10, v22, s[42:43]
	v_cndmask_b32_e64 v13, v13, v25, s[42:43]
	v_cndmask_b32_e64 v12, v12, v24, s[42:43]
	v_add_u32_e32 v0, 0x1000, v0
	s_or_b64 s[46:47], s[44:45], s[46:47]
	v_lshl_add_u64 v[26:27], v[26:27], 0, v[208:209]
	s_waitcnt vmcnt(0)
	v_mov_b32_e32 v18, v2
	v_mov_b32_e32 v19, v4
	v_mov_b32_e32 v4, v3
	s_waitcnt vmcnt(0)
	v_mov_b32_e32 v2, v6
	v_mov_b32_e32 v3, v8
	v_mov_b32_e32 v8, v7
	v_pk_mul_f32 v[6:7], v[18:19], v[10:11]
	v_pk_mul_f32 v[2:3], v[2:3], v[14:15]
	v_pk_mul_f32 v[4:5], v[4:5], v[12:13]
	v_pk_mul_f32 v[8:9], v[8:9], v[16:17]
	v_bfe_u32 v14, v6, 16, 1
	v_bfe_u32 v15, v7, 16, 1
	v_bfe_u32 v16, v2, 16, 1
	v_bfe_u32 v17, v3, 16, 1
	v_bfe_u32 v10, v9, 16, 1
	v_bfe_u32 v11, v8, 16, 1
	v_bfe_u32 v12, v5, 16, 1
	v_bfe_u32 v13, v4, 16, 1
	v_add3_u32 v3, v3, v17, s33
	v_add3_u32 v2, v2, v16, s33
	v_add3_u32 v7, v7, v15, s33
	v_add3_u32 v6, v6, v14, s33
	v_add3_u32 v13, v4, v13, s33
	v_add3_u32 v12, v5, v12, s33
	v_add3_u32 v4, v8, v11, s33
	v_add3_u32 v5, v9, v10, s33
	v_lshrrev_b32_e32 v6, 16, v6
	v_lshrrev_b32_e32 v7, 16, v7
	v_lshrrev_b32_e32 v2, 16, v2
	v_lshrrev_b32_e32 v3, 16, v3
	v_and_or_b32 v5, v5, s54, v3
	v_and_or_b32 v4, v4, s54, v2
	v_and_or_b32 v3, v12, s54, v7
	v_and_or_b32 v2, v13, s54, v6
	global_store_dwordx4 v[26:27], v[2:5], off nt
	s_andn2_b64 exec, exec, s[46:47]
	s_cbranch_execnz .LBB0_201

; __device__ __forceinline__ unsigned pk2(float lo, float hi) { return f2bf(lo) | (f2bf(hi) << 16); }
; __device__ __forceinline__ void s5_gen(LAS unsigned char* lds, const S5In P, int g, int q, bf16_t* Bst, bf16_t* Bout, const int tid) {
;     ...
;     for (int cid = tid; cid < 4096; cid += 512) { const int nl = cid >> 6, k0 = (cid & 63) * 8, n = q * 64 + nl, s = n >> 4, ch = n & 15; float v[8];
;         if (k0 < 256) { const int r = k0 >> 4, c0 = k0 & 15;
; #pragma unroll
;             for (int j = 0; j < 8; ++j) { const int c2 = c0 + j; float t = 0.f;
;                 if (r <= s) t += kt[((0 * 16 + (s - r)) * 16 + ch) * 16 + c2];
;                 if (r >= s) t += kt[((1 * 16 + (r - s)) * 16 + ch) * 16 + c2];
;                 if (r == s && c2 == ch) t += P.dskip[g * 16 + ch];
;                 v[j] = t * P.gain[g * 16 + c2]; }
;         } else { const int kk = k0 - 256, di = kk >> 7, ri = (kk >> 6) & 1, p0 = kk & 63;
; #pragma unroll
;             for (int j = 0; j < 8; ++j) { const int p = p0 + j; const f32x2v C = cc[(di * 16 + ch) * 64 + p], w = pw[(di * 64 + p) * 17 + (di == 0 ? s + 1 : 16 - s)];
;                 v[j] = ri == 0 ? (C.x * w.x - C.y * w.y) : -(C.x * w.y + C.y * w.x); } }
;         u32x4 o; o.x = pk2(v[0], v[1]); o.y = pk2(v[2], v[3]); o.z = pk2(v[4], v[5]); o.w = pk2(v[6], v[7]);
;         *(u32x4*)(Bout + ((size_t)g * 256 + n) * 512 + k0) = o; }
.LBB0_205:
	s_or_b64 exec, exec, s[50:51]
	v_bfe_u32 v9, v0, 16, 1
	v_add3_u32 v0, v0, v9, s33
	v_bfe_u32 v9, v1, 16, 1
	v_lshrrev_b32_e32 v0, 16, v0
	v_add3_u32 v1, v1, v9, s33
	s_mov_b32 s42, 0xffff0000
	v_and_or_b32 v0, v1, s42, v0
	v_bfe_u32 v1, v2, 16, 1
	v_add3_u32 v1, v2, v1, s33
	v_bfe_u32 v2, v3, 16, 1
	v_lshrrev_b32_e32 v1, 16, v1
	v_add3_u32 v2, v3, v2, s33
	v_and_or_b32 v1, v2, s42, v1
	v_bfe_u32 v2, v4, 16, 1
	v_add3_u32 v2, v4, v2, s33
	v_bfe_u32 v3, v5, 16, 1
	v_lshrrev_b32_e32 v2, 16, v2
	v_add3_u32 v3, v5, v3, s33
	v_and_or_b32 v2, v3, s42, v2
	v_bfe_u32 v3, v6, 16, 1
	v_add3_u32 v3, v6, v3, s33
	v_bfe_u32 v4, v7, 16, 1
	v_lshrrev_b32_e32 v3, 16, v3
	v_add3_u32 v4, v7, v4, s33
	v_ashrrev_i32_e32 v9, 31, v8
	v_and_or_b32 v3, v4, s42, v3
	v_lshlrev_b64 v[4:5], 10, v[8:9]
	v_lshl_add_u64 v[4:5], s[16:17], 0, v[4:5]
	v_lshlrev_b32_e32 v208, 1, v12
	v_lshl_add_u64 v[4:5], v[4:5], 0, v[208:209]
	s_movk_i32 s42, 0xdff
	global_store_dwordx4 v[4:5], v[0:3], off nt
	v_cmp_lt_i32_e32 vcc, s42, v11
	v_add_u32_e32 v10, 0x1000, v10
	v_add_u32_e32 v0, 0x200, v11
	s_or_b64 s[48:49], vcc, s[48:49]
	v_mov_b32_e32 v11, v0
	s_andn2_b64 exec, exec, s[48:49]
	s_cbranch_execz .LBB0_191

; #define LAS __attribute__((address_space(3)))
; __device__ __forceinline__ void conv_item(const float* W, int ldw, int K, int c0, int k0, const float* gain, bf16_t* Wt, int n0, LAS float* scr, int lane) {
;     f32x4 v[16];
;     const int kr = lane >> 4, n4 = (lane & 15) * 4;
;     const float* src = W + (size_t)(k0 + kr) * ldw + c0 + n4;
; #pragma unroll
;     for (int i = 0; i < 16; ++i) v[i] = __builtin_nontemporal_load((const f32x4*)(src + (size_t)(4 * i) * ldw));
;     if (gain) {
; #pragma unroll
;         for (int i = 0; i < 16; ++i) v[i] = v[i] * gain[k0 + 4 * i + kr];
;     }
; #pragma unroll
;     for (int i = 0; i < 16; ++i) { const int k = 4 * i + kr; *(LAS f32x4*)(scr + k * 64 + (n4 ^ (((k >> 3) & 7) << 2))) = v[i]; }
; __device__ __forceinline__ int map_col(int kind, int arg, int n0) {
;     if (kind == MAP_GLU) { const int pn = n0 >> 8, w = n0 & 255; return (w >> 7) * 1024 + pn * 128 + (w & 127); }
.LBB0_259:
	s_ashr_i32 s2, s17, 31
	s_lshr_b32 s2, s2, 27
	s_add_i32 s2, s17, s2
	s_ashr_i32 s2, s2, 5
	s_lshl_b32 s3, s2, 11
	s_lshl_b32 s19, s2, 10
	s_lshl_b32 s2, s2, 6
	s_sub_i32 s18, s5, s3
	s_sub_i32 s3, s13, s3
	s_sub_i32 s19, s15, s19
	v_or_b32_e32 v0, s2, v34
	s_and_b32 s3, s3, 0x400
	s_and_b32 s19, s19, 0xffffff80
	s_and_b32 s20, s18, 64
	v_ashrrev_i32_e32 v1, 31, v0
	s_add_i32 s3, s3, s19
	v_lshlrev_b64 v[0:1], 13, v[0:1]
	s_or_b32 s20, s3, s20
	v_lshl_add_u64 v[0:1], s[0:1], 0, v[0:1]
	s_ashr_i32 s21, s20, 31
	v_lshl_add_u64 v[0:1], s[20:21], 2, v[0:1]
	v_lshl_add_u64 v[4:5], v[0:1], 0, v[208:209]
	v_add_co_u32_e32 v6, vcc, s27, v4
	global_load_dwordx4 v[0:3], v[4:5], off nt
	s_nop 0
	v_addc_co_u32_e32 v7, vcc, 0, v5, vcc
	v_add_co_u32_e32 v8, vcc, s29, v4
	s_mov_b32 s3, 0x68000
	s_nop 0
	v_addc_co_u32_e32 v9, vcc, 0, v5, vcc
	v_add_co_u32_e32 v12, vcc, s30, v4
	s_add_i32 s17, s17, s26
	s_nop 0
	v_addc_co_u32_e32 v13, vcc, 0, v5, vcc
	v_add_co_u32_e32 v14, vcc, s31, v4
	s_add_i32 s5, s5, s12
	s_nop 0
	v_addc_co_u32_e32 v15, vcc, 0, v5, vcc
	v_add_co_u32_e32 v20, vcc, s36, v4
	s_add_i32 s13, s13, s14
	s_nop 0
	v_addc_co_u32_e32 v21, vcc, 0, v5, vcc
	v_add_co_u32_e32 v22, vcc, s37, v4
	s_add_i32 s15, s15, s16
	s_nop 0
	v_addc_co_u32_e32 v23, vcc, 0, v5, vcc
	v_add_co_u32_e32 v30, vcc, s38, v4
	s_mov_b32 s20, s28
	s_nop 0
	v_addc_co_u32_e32 v31, vcc, 0, v5, vcc
	v_add_co_u32_e32 v32, vcc, s40, v4
	s_nop 1
	v_addc_co_u32_e32 v33, vcc, 0, v5, vcc
	v_add_co_u32_e32 v72, vcc, s39, v4
	s_nop 1
	v_addc_co_u32_e32 v73, vcc, 0, v5, vcc
	v_add_co_u32_e32 v74, vcc, s41, v4
	s_nop 1
	v_addc_co_u32_e32 v75, vcc, 0, v5, vcc
	v_add_co_u32_e32 v76, vcc, s42, v4
	s_nop 1
	v_addc_co_u32_e32 v77, vcc, 0, v5, vcc
	v_add_co_u32_e32 v78, vcc, s43, v4
	s_nop 1
	v_addc_co_u32_e32 v79, vcc, 0, v5, vcc
	v_add_co_u32_e32 v80, vcc, s3, v4
	s_mov_b32 s3, 0x78000
	s_nop 0
	v_addc_co_u32_e32 v81, vcc, 0, v5, vcc
	v_add_co_u32_e32 v82, vcc, s44, v4
	s_nop 1
	v_addc_co_u32_e32 v83, vcc, 0, v5, vcc
	v_add_co_u32_e32 v84, vcc, s3, v4
	s_ashr_i32 s3, s2, 31
	s_nop 0
	v_addc_co_u32_e32 v85, vcc, 0, v5, vcc
	global_load_dwordx4 v[4:7], v[6:7], off nt
	s_nop 0
	global_load_dwordx4 v[8:11], v[8:9], off nt
	s_nop 0
	global_load_dwordx4 v[16:19], v[12:13], off nt
	global_load_dwordx4 v[24:27], v[14:15], off nt
	global_load_dwordx4 v[52:55], v[20:21], off nt
	global_load_dwordx4 v[56:59], v[22:23], off nt
	s_cmpk_gt_i32 s17, 0x1ff
	s_waitcnt vmcnt(0)
	ds_write_b128 v35, v[0:3]
	global_load_dwordx4 v[60:63], v[30:31], off nt
	global_load_dwordx4 v[68:71], v[32:33], off nt
	v_add_u32_e32 v32, s18, v43
	v_ashrrev_i32_e32 v33, 31, v32
	v_lshl_add_u64 v[30:31], s[2:3], 1, v[28:29]
	s_waitcnt vmcnt(7)
	ds_write_b128 v35, v[4:7] offset:1024
	global_load_dwordx4 v[0:3], v[72:73], off nt
	global_load_dwordx4 v[4:7], v[74:75], off nt
	s_waitcnt vmcnt(8)
	ds_write_b128 v36, v[8:11] offset:2048
	global_load_dwordx4 v[8:11], v[76:77], off nt
	global_load_dwordx4 v[12:15], v[78:79], off nt
	s_waitcnt vmcnt(9)
	ds_write_b128 v36, v[16:19] offset:3072
	global_load_dwordx4 v[16:19], v[80:81], off nt
	global_load_dwordx4 v[20:23], v[82:83], off nt
	s_waitcnt vmcnt(10)
	ds_write_b128 v37, v[24:27] offset:4096
	global_load_dwordx4 v[24:27], v[84:85], off nt
	s_waitcnt vmcnt(10)
	ds_write_b128 v37, v[52:55] offset:5120
	s_waitcnt vmcnt(9)
	ds_write_b128 v38, v[56:59] offset:6144
	v_add_u32_e32 v52, 8, v32
	v_ashrrev_i32_e32 v53, 31, v52
	s_waitcnt vmcnt(8)
	ds_write_b128 v38, v[60:63] offset:7168
	s_waitcnt vmcnt(7)
	ds_write_b128 v39, v[68:71] offset:8192
	v_lshlrev_b64 v[68:69], 11, v[32:33]
	v_lshl_add_u64 v[68:69], v[30:31], 0, v[68:69]
	v_lshlrev_b64 v[52:53], 11, v[52:53]
	v_add_u32_e32 v54, 16, v32
	v_lshl_add_u64 v[52:53], v[30:31], 0, v[52:53]
	v_ashrrev_i32_e32 v55, 31, v54
	v_lshlrev_b64 v[54:55], 11, v[54:55]
	v_add_u32_e32 v56, 24, v32
	v_lshl_add_u64 v[54:55], v[30:31], 0, v[54:55]
	v_ashrrev_i32_e32 v57, 31, v56
	v_lshlrev_b64 v[56:57], 11, v[56:57]
	v_add_u32_e32 v58, 32, v32
	v_lshl_add_u64 v[56:57], v[30:31], 0, v[56:57]
	s_waitcnt vmcnt(6)
	ds_write_b128 v39, v[0:3] offset:9216
	s_waitcnt vmcnt(5)
	ds_write_b128 v40, v[4:7] offset:10240
	s_waitcnt vmcnt(4)
	ds_write_b128 v40, v[8:11] offset:11264
	s_waitcnt vmcnt(3)
	ds_write_b128 v41, v[12:15] offset:12288
	s_waitcnt vmcnt(2)
; __device__ __forceinline__ unsigned cvt_pk_bf16(float lo, float hi) { unsigned r; asm volatile("v_cvt_pk_bf16_f32 %0, %1, %2" : "=v"(r) : "v"(lo), "v"(hi)); return r; }
; #define LAS __attribute__((address_space(3)))
; #define LDS_WAIT() asm volatile("s_waitcnt lgkmcnt(0)" ::: "memory")
; __device__ __forceinline__ void conv_item(const float* W, int ldw, int K, int c0, int k0, const float* gain, bf16_t* Wt, int n0, LAS float* scr, int lane) {
;     ...
;     for (int i = 0; i < 16; ++i) { const int k = 4 * i + kr; *(LAS f32x4*)(scr + k * 64 + (n4 ^ (((k >> 3) & 7) << 2))) = v[i]; }
;     LDS_WAIT(); asm volatile("" ::: "memory");
;     const int c = lane & 7;
; #pragma unroll
;     for (int j = 0; j < 8; ++j) { const int n = (lane >> 3) + 8 * j; const LAS float* s = scr + (8 * c) * 64 + (n ^ (c << 2));
;         u32x4 o; o.x = pg8::cvt_pk_bf16(s[0 * 64], s[1 * 64]); o.y = pg8::cvt_pk_bf16(s[2 * 64], s[3 * 64]); o.z = pg8::cvt_pk_bf16(s[4 * 64], s[5 * 64]); o.w = pg8::cvt_pk_bf16(s[6 * 64], s[7 * 64]);
;         *(u32x4*)(Wt + (size_t)(n0 + n) * K + k0 + 8 * c) = o; }
;     LDS_WAIT(); asm volatile("" ::: "memory");
	ds_write_b128 v41, v[16:19] offset:13312
	s_waitcnt vmcnt(1)
	ds_write_b128 v42, v[20:23] offset:14336
	s_waitcnt vmcnt(0)
	ds_write_b128 v42, v[24:27] offset:15360
	s_waitcnt lgkmcnt(0)
	ds_read2st64_b32 v[0:1], v44 offset1:1
	s_waitcnt lgkmcnt(0)
	v_cvt_pk_bf16_f32 v0, v0, v1
	ds_read2st64_b32 v[2:3], v44 offset0:2 offset1:3
	s_waitcnt lgkmcnt(0)
	v_cvt_pk_bf16_f32 v1, v2, v3
	ds_read2st64_b32 v[2:3], v44 offset0:4 offset1:5
	s_waitcnt lgkmcnt(0)
	v_cvt_pk_bf16_f32 v2, v2, v3
	ds_read2st64_b32 v[4:5], v44 offset0:6 offset1:7
	s_waitcnt lgkmcnt(0)
	v_cvt_pk_bf16_f32 v3, v4, v5
	ds_read2st64_b32 v[4:5], v45 offset1:1
	global_store_dwordx4 v[68:69], v[0:3], off nt
	v_ashrrev_i32_e32 v59, 31, v58
	v_lshlrev_b64 v[58:59], 11, v[58:59]
	s_waitcnt lgkmcnt(0)
	v_cvt_pk_bf16_f32 v0, v4, v5
	ds_read2st64_b32 v[2:3], v45 offset0:2 offset1:3
	s_waitcnt lgkmcnt(0)
	v_cvt_pk_bf16_f32 v1, v2, v3
	ds_read2st64_b32 v[2:3], v45 offset0:4 offset1:5
	s_waitcnt lgkmcnt(0)
	v_cvt_pk_bf16_f32 v2, v2, v3
	ds_read2st64_b32 v[4:5], v45 offset0:6 offset1:7
	s_waitcnt lgkmcnt(0)
	v_cvt_pk_bf16_f32 v3, v4, v5
	ds_read2st64_b32 v[4:5], v46 offset1:1
	global_store_dwordx4 v[52:53], v[0:3], off nt
	v_add_u32_e32 v60, 40, v32
	v_lshl_add_u64 v[58:59], v[30:31], 0, v[58:59]
	s_waitcnt lgkmcnt(0)
	v_cvt_pk_bf16_f32 v0, v4, v5
	ds_read2st64_b32 v[2:3], v46 offset0:2 offset1:3
	s_waitcnt lgkmcnt(0)
	v_cvt_pk_bf16_f32 v1, v2, v3
	ds_read2st64_b32 v[2:3], v46 offset0:4 offset1:5
	s_waitcnt lgkmcnt(0)
	v_cvt_pk_bf16_f32 v2, v2, v3
	ds_read2st64_b32 v[4:5], v46 offset0:6 offset1:7
	s_waitcnt lgkmcnt(0)
	v_cvt_pk_bf16_f32 v3, v4, v5
	ds_read2st64_b32 v[4:5], v47 offset1:1
	global_store_dwordx4 v[54:55], v[0:3], off nt
	v_ashrrev_i32_e32 v61, 31, v60
	v_lshlrev_b64 v[60:61], 11, v[60:61]
	s_waitcnt lgkmcnt(0)
	v_cvt_pk_bf16_f32 v0, v4, v5
	ds_read2st64_b32 v[2:3], v47 offset0:2 offset1:3
	s_waitcnt lgkmcnt(0)
	v_cvt_pk_bf16_f32 v1, v2, v3
	ds_read2st64_b32 v[2:3], v47 offset0:4 offset1:5
	s_waitcnt lgkmcnt(0)
	v_cvt_pk_bf16_f32 v2, v2, v3
	ds_read2st64_b32 v[4:5], v47 offset0:6 offset1:7
	s_waitcnt lgkmcnt(0)
	v_cvt_pk_bf16_f32 v3, v4, v5
	ds_read2st64_b32 v[4:5], v48 offset1:1
	global_store_dwordx4 v[56:57], v[0:3], off nt
	v_add_u32_e32 v62, 48, v32
	v_lshl_add_u64 v[60:61], v[30:31], 0, v[60:61]
	s_waitcnt lgkmcnt(0)
	v_cvt_pk_bf16_f32 v0, v4, v5
	ds_read2st64_b32 v[2:3], v48 offset0:2 offset1:3
	s_waitcnt lgkmcnt(0)
	v_cvt_pk_bf16_f32 v1, v2, v3
	ds_read2st64_b32 v[2:3], v48 offset0:4 offset1:5
	s_waitcnt lgkmcnt(0)
	v_cvt_pk_bf16_f32 v2, v2, v3
	ds_read2st64_b32 v[4:5], v48 offset0:6 offset1:7
	s_waitcnt lgkmcnt(0)
	v_cvt_pk_bf16_f32 v3, v4, v5
	ds_read2st64_b32 v[4:5], v49 offset1:1
	global_store_dwordx4 v[58:59], v[0:3], off nt
	v_ashrrev_i32_e32 v63, 31, v62
	v_lshlrev_b64 v[62:63], 11, v[62:63]
	s_waitcnt lgkmcnt(0)
	v_cvt_pk_bf16_f32 v0, v4, v5
	ds_read2st64_b32 v[2:3], v49 offset0:2 offset1:3
	s_waitcnt lgkmcnt(0)
	v_cvt_pk_bf16_f32 v1, v2, v3
	ds_read2st64_b32 v[2:3], v49 offset0:4 offset1:5
	s_waitcnt lgkmcnt(0)
	v_cvt_pk_bf16_f32 v2, v2, v3
	ds_read2st64_b32 v[4:5], v49 offset0:6 offset1:7
	s_waitcnt lgkmcnt(0)
	v_cvt_pk_bf16_f32 v3, v4, v5
	ds_read2st64_b32 v[4:5], v50 offset1:1
	global_store_dwordx4 v[60:61], v[0:3], off nt
	v_add_u32_e32 v6, 56, v32
	v_lshl_add_u64 v[62:63], v[30:31], 0, v[62:63]
	s_waitcnt lgkmcnt(0)
	v_cvt_pk_bf16_f32 v0, v4, v5
	ds_read2st64_b32 v[2:3], v50 offset0:2 offset1:3
	s_waitcnt lgkmcnt(0)
	v_cvt_pk_bf16_f32 v1, v2, v3
	ds_read2st64_b32 v[2:3], v50 offset0:4 offset1:5
	s_waitcnt lgkmcnt(0)
	v_cvt_pk_bf16_f32 v2, v2, v3
	ds_read2st64_b32 v[4:5], v50 offset0:6 offset1:7
	s_waitcnt lgkmcnt(0)
	v_cvt_pk_bf16_f32 v3, v4, v5
	v_ashrrev_i32_e32 v7, 31, v6
	ds_read2st64_b32 v[4:5], v51 offset1:1
	global_store_dwordx4 v[62:63], v[0:3], off nt
	v_lshlrev_b64 v[6:7], 11, v[6:7]
	v_lshl_add_u64 v[6:7], v[30:31], 0, v[6:7]
	s_waitcnt lgkmcnt(0)
	v_cvt_pk_bf16_f32 v0, v4, v5
	ds_read2st64_b32 v[2:3], v51 offset0:2 offset1:3
	s_waitcnt lgkmcnt(0)
	v_cvt_pk_bf16_f32 v1, v2, v3
	ds_read2st64_b32 v[2:3], v51 offset0:4 offset1:5
	s_waitcnt lgkmcnt(0)
	v_cvt_pk_bf16_f32 v2, v2, v3
	ds_read2st64_b32 v[4:5], v51 offset0:6 offset1:7
	s_waitcnt lgkmcnt(0)
	v_cvt_pk_bf16_f32 v3, v4, v5
	global_store_dwordx4 v[6:7], v[0:3], off nt
	s_waitcnt lgkmcnt(0)
	s_cbranch_scc0 .LBB0_259

; __device__ __forceinline__ unsigned cvt_pk_bf16(float lo, float hi) { unsigned r; asm volatile("v_cvt_pk_bf16_f32 %0, %1, %2" : "=v"(r) : "v"(lo), "v"(hi)); return r; }
; #define LAS __attribute__((address_space(3)))
; template <bool F32SRC> __device__ __forceinline__ void unorm_chunk(LAS unsigned char* lds, const float* xsrc, bf16_t* hbio, bf16_t* Ug, int chunk, const int tid) {
;     ...
;         } else { const u32x4* xr = (const u32x4*)(hbio + row * DM) + lane; u32x4 w[2]; float v[16]; float ss = 0.f;
; #pragma unroll
;             for (int j = 0; j < 2; ++j) { w[j] = xr[64 * j];
;                 v[8 * j + 0] = __uint_as_float(w[j].x << 16); v[8 * j + 1] = __uint_as_float(w[j].x & 0xffff0000u); v[8 * j + 2] = __uint_as_float(w[j].y << 16); v[8 * j + 3] = __uint_as_float(w[j].y & 0xffff0000u);
;                 v[8 * j + 4] = __uint_as_float(w[j].z << 16); v[8 * j + 5] = __uint_as_float(w[j].z & 0xffff0000u); v[8 * j + 6] = __uint_as_float(w[j].w << 16); v[8 * j + 7] = __uint_as_float(w[j].w & 0xffff0000u); }
; #pragma unroll
;             for (int i = 0; i < 16; ++i) ss += v[i] * v[i];
;             const float rstd = rsqrtf(wsum_l(ss, lane) * (1.0f / DM) + EPS);
; #pragma unroll
;             for (int j = 0; j < 2; ++j) { u32x4 q; q.x = pg8::cvt_pk_bf16(v[8 * j] * rstd, v[8 * j + 1] * rstd); q.y = pg8::cvt_pk_bf16(v[8 * j + 2] * rstd, v[8 * j + 3] * rstd);
;                 q.z = pg8::cvt_pk_bf16(v[8 * j + 4] * rstd, v[8 * j + 5] * rstd); q.w = pg8::cvt_pk_bf16(v[8 * j + 6] * rstd, v[8 * j + 7] * rstd); *(LAS u32x4*)(T + s * 2080 + (64 * j + lane) * 16) = q; } }
.LBB0_307:
	v_readfirstlane_b32 s0, v66
	s_ashr_i32 s1, s0, 6
	s_lshl_b32 s0, s1, 1
	s_mul_i32 s3, s1, 0x1040
	v_lshl_or_b32 v14, s1, 3, v11
	s_ashr_i32 s1, s0, 31
	s_lshl_b64 s[10:11], s[0:1], 11
	s_add_u32 s10, s24, s10
	v_ashrrev_i32_e32 v15, 31, v14
	s_addc_u32 s11, s25, s11
	v_lshl_add_u32 v38, v14, 5, v12
	v_or_b32_e32 v26, 2, v14
	v_or_b32_e32 v28, 4, v14
	v_or_b32_e32 v30, 6, v14
	v_lshlrev_b64 v[32:33], 19, v[14:15]
	v_lshl_add_u64 v[14:15], s[10:11], 0, v[2:3]
	v_add_co_u32_e32 v22, vcc, s18, v14
	v_add_u32_e32 v13, s3, v10
	s_nop 0
	v_addc_co_u32_e32 v23, vcc, 0, v15, vcc
	global_load_dwordx4 v[14:17], v[22:23], off
	global_load_dwordx4 v[18:21], v[22:23], off offset:1024
	s_or_b32 s0, s0, 1
	s_mulk_i32 s0, 0x820
	v_lshl_add_u64 v[32:33], v[0:1], 0, v[32:33]
	v_lshl_add_u64 v[32:33], s[24:25], 0, v[32:33]
	s_add_i32 s2, s2, s12
	v_lshl_add_u64 v[2:3], v[2:3], 0, s[16:17]
	s_cmpk_lt_i32 s2, 0x400
	s_waitcnt vmcnt(0)
	v_and_b32_e32 v25, 0xffff0000, v14
	v_lshlrev_b32_e32 v24, 16, v14
	v_mul_f32_e32 v42, v25, v25
	v_lshlrev_b32_e32 v27, 16, v15
	v_fmac_f32_e32 v42, v24, v24
	v_and_b32_e32 v29, 0xffff0000, v15
	v_fmac_f32_e32 v42, v27, v27
	v_lshlrev_b32_e32 v31, 16, v16
	v_fmac_f32_e32 v42, v29, v29
	v_and_b32_e32 v34, 0xffff0000, v16
	v_fmac_f32_e32 v42, v31, v31
	v_lshlrev_b32_e32 v35, 16, v17
	v_fmac_f32_e32 v42, v34, v34
	v_and_b32_e32 v36, 0xffff0000, v17
	v_fmac_f32_e32 v42, v35, v35
	s_waitcnt vmcnt(0)
	v_lshlrev_b32_e32 v37, 16, v18
	v_fmac_f32_e32 v42, v36, v36
	v_and_b32_e32 v39, 0xffff0000, v18
	v_fmac_f32_e32 v42, v37, v37
	v_lshlrev_b32_e32 v40, 16, v19
	v_fmac_f32_e32 v42, v39, v39
	v_and_b32_e32 v41, 0xffff0000, v19
	v_and_b32_e32 v14, 0xffff0000, v20
	v_lshlrev_b32_e32 v15, 16, v20
	v_fmac_f32_e32 v42, v40, v40
	v_pk_mul_f32 v[18:19], v[14:15], v[14:15]
	v_fmac_f32_e32 v42, v41, v41
	v_and_b32_e32 v16, 0xffff0000, v21
	v_lshlrev_b32_e32 v17, 16, v21
	v_add_f32_e32 v19, v19, v42
	v_pk_mul_f32 v[20:21], v[16:17], v[16:17]
	v_add_f32_e32 v18, v18, v19
	v_add_f32_e32 v18, v21, v18
	v_add_f32_e32 v18, v20, v18
	ds_bpermute_b32 v19, v4, v18
	s_waitcnt lgkmcnt(0)
	v_add_f32_e32 v18, v18, v19
	ds_bpermute_b32 v19, v5, v18
	s_waitcnt lgkmcnt(0)
	v_add_f32_e32 v18, v18, v19
	ds_bpermute_b32 v19, v6, v18
	s_waitcnt lgkmcnt(0)
	v_add_f32_e32 v18, v18, v19
	ds_bpermute_b32 v19, v7, v18
	s_waitcnt lgkmcnt(0)
	v_add_f32_e32 v18, v18, v19
	ds_bpermute_b32 v19, v8, v18
	s_waitcnt lgkmcnt(0)
	v_add_f32_e32 v18, v18, v19
	ds_bpermute_b32 v19, v9, v18
	s_waitcnt lgkmcnt(0)
	v_add_f32_e32 v18, v18, v19
	v_fmamk_f32 v18, v18, 0x3a800000, v226
	v_mul_f32_e32 v19, 0x4b800000, v18
	v_cmp_gt_f32_e32 vcc, s5, v18
	s_nop 1
	v_cndmask_b32_e32 v18, v18, v19, vcc
	v_rsq_f32_e32 v18, v18
	s_nop 0
	v_mul_f32_e32 v19, 0x45800000, v18
	v_cndmask_b32_e32 v18, v18, v19, vcc
	v_mul_f32_e32 v19, v18, v24
	v_mul_f32_e32 v20, v18, v25
	v_mul_f32_e32 v21, v18, v27
	v_mul_f32_e32 v24, v18, v29
	v_mul_f32_e32 v25, v18, v31
	v_mul_f32_e32 v27, v18, v34
	v_mul_f32_e32 v29, v18, v35
	v_mul_f32_e32 v31, v18, v36
	v_mul_f32_e32 v34, v18, v37
	v_mul_f32_e32 v35, v18, v39
	v_mul_f32_e32 v36, v18, v40
	v_mul_f32_e32 v37, v18, v41
	v_mul_f32_e32 v39, v18, v15
	v_mul_f32_e32 v40, v18, v14
	v_mul_f32_e32 v41, v18, v17
	v_mul_f32_e32 v18, v18, v16
	v_cvt_pk_bf16_f32 v14, v19, v20
	v_cvt_pk_bf16_f32 v15, v21, v24
	v_cvt_pk_bf16_f32 v16, v25, v27
	v_cvt_pk_bf16_f32 v17, v29, v31
	ds_write_b128 v13, v[14:17]
	v_cvt_pk_bf16_f32 v14, v34, v35
	v_cvt_pk_bf16_f32 v15, v36, v37
	v_cvt_pk_bf16_f32 v16, v39, v40
	v_cvt_pk_bf16_f32 v17, v41, v18
	global_load_dwordx4 v[18:21], v[22:23], off offset:2048
	s_nop 0
	global_load_dwordx4 v[22:25], v[22:23], off offset:3072
	v_ashrrev_i32_e32 v27, 31, v26
	v_lshl_add_u32 v39, v26, 5, v12
	v_lshlrev_b64 v[26:27], 19, v[26:27]
	v_ashrrev_i32_e32 v29, 31, v28
	v_lshl_add_u64 v[26:27], v[0:1], 0, v[26:27]
	v_lshl_add_u32 v40, v28, 5, v12
	v_lshlrev_b64 v[28:29], 19, v[28:29]
	v_lshl_add_u64 v[34:35], s[24:25], 0, v[26:27]
	v_lshl_add_u64 v[28:29], v[0:1], 0, v[28:29]
	ds_write_b128 v13, v[14:17] offset:1024
	v_lshl_add_u64 v[36:37], s[24:25], 0, v[28:29]
	v_add_u32_e32 v26, s0, v10
	v_lshl_add_u32 v41, v30, 5, v12
	v_ashrrev_i32_e32 v31, 31, v30
	v_lshlrev_b64 v[30:31], 19, v[30:31]
	v_lshl_add_u64 v[30:31], v[0:1], 0, v[30:31]
	v_lshl_add_u64 v[30:31], s[24:25], 0, v[30:31]
	v_lshl_add_u64 v[0:1], v[0:1], 0, s[14:15]
	s_waitcnt vmcnt(1)
; __device__ __forceinline__ unsigned cvt_pk_bf16(float lo, float hi) { unsigned r; asm volatile("v_cvt_pk_bf16_f32 %0, %1, %2" : "=v"(r) : "v"(lo), "v"(hi)); return r; }
; #define LAS __attribute__((address_space(3)))
; #define LDS_WAIT() asm volatile("s_waitcnt lgkmcnt(0)" ::: "memory")
; template <bool F32SRC> __device__ __forceinline__ void unorm_chunk(LAS unsigned char* lds, const float* xsrc, bf16_t* hbio, bf16_t* Ug, int chunk, const int tid) {
;     ...
;             for (int i = 0; i < 16; ++i) ss += v[i] * v[i];
;             const float rstd = rsqrtf(wsum_l(ss, lane) * (1.0f / DM) + EPS);
; #pragma unroll
;             for (int j = 0; j < 2; ++j) { u32x4 q; q.x = pg8::cvt_pk_bf16(v[8 * j] * rstd, v[8 * j + 1] * rstd); q.y = pg8::cvt_pk_bf16(v[8 * j + 2] * rstd, v[8 * j + 3] * rstd);
;                 q.z = pg8::cvt_pk_bf16(v[8 * j + 4] * rstd, v[8 * j + 5] * rstd); q.w = pg8::cvt_pk_bf16(v[8 * j + 6] * rstd, v[8 * j + 7] * rstd); *(LAS u32x4*)(T + s * 2080 + (64 * j + lane) * 16) = q; } }
;     }
;     LDS_WAIT(); __syncthreads();
; #pragma unroll
;     for (int i = 0; i < 4; ++i) { const int gq = 8 * wid + 2 * i + (lane >> 5), l = lane & 31, s = l >> 1, hf = l & 1;
;         const u32x4 q = *(const LAS u32x4*)(T + s * 2080 + gq * 32 + hf * 16);
;         *(u32x4*)(Ug + ((size_t)gq * 1024 + chunk) * 256 + l * 8) = q; }
	v_and_b32_e32 v27, 0xffff0000, v18
	v_lshlrev_b32_e32 v13, 16, v18
	s_waitcnt vmcnt(0)
	v_and_b32_e32 v14, 0xffff0000, v24
	v_lshlrev_b32_e32 v15, 16, v24
	v_mul_f32_e32 v24, v27, v27
	v_lshlrev_b32_e32 v28, 16, v19
	v_fmac_f32_e32 v24, v13, v13
	v_and_b32_e32 v29, 0xffff0000, v19
	v_fmac_f32_e32 v24, v28, v28
	v_lshlrev_b32_e32 v42, 16, v20
	v_fmac_f32_e32 v24, v29, v29
	v_and_b32_e32 v43, 0xffff0000, v20
	v_fmac_f32_e32 v24, v42, v42
	v_lshlrev_b32_e32 v44, 16, v21
	v_fmac_f32_e32 v24, v43, v43
	v_and_b32_e32 v45, 0xffff0000, v21
	v_fmac_f32_e32 v24, v44, v44
	v_lshlrev_b32_e32 v46, 16, v22
	v_fmac_f32_e32 v24, v45, v45
	v_and_b32_e32 v22, 0xffff0000, v22
	v_fmac_f32_e32 v24, v46, v46
	v_lshlrev_b32_e32 v47, 16, v23
	v_fmac_f32_e32 v24, v22, v22
	v_and_b32_e32 v23, 0xffff0000, v23
	v_fmac_f32_e32 v24, v47, v47
	v_pk_mul_f32 v[18:19], v[14:15], v[14:15]
	v_fmac_f32_e32 v24, v23, v23
	v_and_b32_e32 v16, 0xffff0000, v25
	v_lshlrev_b32_e32 v17, 16, v25
	v_add_f32_e32 v19, v19, v24
	v_pk_mul_f32 v[20:21], v[16:17], v[16:17]
	v_add_f32_e32 v18, v18, v19
	v_add_f32_e32 v18, v21, v18
	v_add_f32_e32 v18, v20, v18
	ds_bpermute_b32 v19, v4, v18
	s_waitcnt lgkmcnt(0)
	v_add_f32_e32 v18, v18, v19
	ds_bpermute_b32 v19, v5, v18
	s_waitcnt lgkmcnt(0)
	v_add_f32_e32 v18, v18, v19
	ds_bpermute_b32 v19, v6, v18
	s_waitcnt lgkmcnt(0)
	v_add_f32_e32 v18, v18, v19
	ds_bpermute_b32 v19, v7, v18
	s_waitcnt lgkmcnt(0)
	v_add_f32_e32 v18, v18, v19
	ds_bpermute_b32 v19, v8, v18
	s_waitcnt lgkmcnt(0)
	v_add_f32_e32 v18, v18, v19
	ds_bpermute_b32 v19, v9, v18
	s_waitcnt lgkmcnt(0)
	v_add_f32_e32 v18, v18, v19
	v_fmamk_f32 v18, v18, 0x3a800000, v226
	v_mul_f32_e32 v19, 0x4b800000, v18
	v_cmp_gt_f32_e32 vcc, s5, v18
	s_nop 1
	v_cndmask_b32_e32 v18, v18, v19, vcc
	v_rsq_f32_e32 v18, v18
	s_nop 0
	v_mul_f32_e32 v19, 0x45800000, v18
	v_cndmask_b32_e32 v18, v18, v19, vcc
	v_mul_f32_e32 v13, v18, v13
	v_mul_f32_e32 v19, v18, v27
	v_mul_f32_e32 v20, v18, v28
	v_mul_f32_e32 v21, v18, v29
	v_mul_f32_e32 v24, v18, v42
	v_mul_f32_e32 v25, v18, v43
	v_mul_f32_e32 v27, v18, v44
	v_mul_f32_e32 v28, v18, v45
	v_mul_f32_e32 v29, v18, v46
	v_mul_f32_e32 v22, v18, v22
	v_mul_f32_e32 v42, v18, v47
	v_mul_f32_e32 v23, v18, v23
	v_mul_f32_e32 v43, v18, v15
	v_mul_f32_e32 v44, v18, v14
	v_mul_f32_e32 v45, v18, v17
	v_mul_f32_e32 v18, v18, v16
	v_cvt_pk_bf16_f32 v14, v13, v19
	v_cvt_pk_bf16_f32 v15, v20, v21
	v_cvt_pk_bf16_f32 v16, v24, v25
	v_cvt_pk_bf16_f32 v17, v27, v28
	ds_write_b128 v26, v[14:17]
	v_cvt_pk_bf16_f32 v14, v29, v22
	v_cvt_pk_bf16_f32 v15, v42, v23
	v_cvt_pk_bf16_f32 v16, v43, v44
	v_cvt_pk_bf16_f32 v17, v45, v18
	ds_write_b128 v26, v[14:17] offset:1024
	s_waitcnt lgkmcnt(0)
	s_waitcnt lgkmcnt(0)
	s_barrier
	ds_read_b128 v[14:17], v38
	ds_read_b128 v[18:21], v39
	ds_read_b128 v[22:25], v40
	ds_read_b128 v[26:29], v41
	s_waitcnt lgkmcnt(3)
	global_store_dwordx4 v[32:33], v[14:17], off nt
	s_waitcnt lgkmcnt(2)
	global_store_dwordx4 v[34:35], v[18:21], off nt
	s_waitcnt lgkmcnt(1)
	global_store_dwordx4 v[36:37], v[22:25], off nt
	s_waitcnt lgkmcnt(0)
	global_store_dwordx4 v[30:31], v[26:29], off nt
	s_waitcnt lgkmcnt(0)
	s_barrier
	s_cbranch_scc1 .LBB0_307

; __device__ __forceinline__ unsigned cvt_pk_bf16(float lo, float hi) { unsigned r; asm volatile("v_cvt_pk_bf16_f32 %0, %1, %2" : "=v"(r) : "v"(lo), "v"(hi)); return r; }
; #define LAS __attribute__((address_space(3)))
; template <bool F32SRC> __device__ __forceinline__ void unorm_chunk(LAS unsigned char* lds, const float* xsrc, bf16_t* hbio, bf16_t* Ug, int chunk, const int tid) {
;     ...
;         if (F32SRC) { const f32x4* xr = (const f32x4*)(xsrc + row * DM) + lane; f32x4 v[4]; float ss = 0.f;
; #pragma unroll
;             for (int j = 0; j < 4; ++j) { v[j] = __builtin_nontemporal_load(xr + 64 * j); ss += (v[j].x * v[j].x + v[j].y * v[j].y) + (v[j].z * v[j].z + v[j].w * v[j].w); }
;             const float rstd = rsqrtf(wsum_l(ss, lane) * (1.0f / DM) + EPS);
;             u32x2* o = (u32x2*)(hbio + row * DM) + lane;
; #pragma unroll
;             for (int j = 0; j < 4; ++j) { u32x2 w; w.x = pg8::cvt_pk_bf16(v[j].x, v[j].y); w.y = pg8::cvt_pk_bf16(v[j].z, v[j].w); o[64 * j] = w;
;                 u32x2 q; q.x = pg8::cvt_pk_bf16(v[j].x * rstd, v[j].y * rstd); q.y = pg8::cvt_pk_bf16(v[j].z * rstd, v[j].w * rstd); *(LAS u32x2*)(T + s * 2080 + (64 * j + lane) * 8) = q; }
.LBB0_312:
	ds_read_b64 v[6:7], v236
	ds_read_b64 v[8:9], v236
	v_readfirstlane_b32 s0, v66
	s_ashr_i32 s1, s0, 6
	s_lshl_b32 s0, s1, 1
	s_mul_i32 s3, s1, 0x1040
	s_mov_b32 s2, s97
	v_lshl_or_b32 v20, s1, 3, v16
	s_ashr_i32 s1, s0, 31
	v_add_u32_e32 v19, s3, v18
	s_waitcnt lgkmcnt(0)
	v_readfirstlane_b32 s3, v7
	s_waitcnt lgkmcnt(0)
	v_readfirstlane_b32 s96, v8
	s_lshl_b64 s[10:11], s[0:1], 12
	s_or_b64 s[2:3], s[96:97], s[2:3]
	s_add_u32 s2, s2, s10
	v_ashrrev_i32_e32 v21, 31, v20
	v_or_b32_e32 v22, 2, v20
	s_addc_u32 s3, s3, s11
	v_lshl_add_u32 v60, v20, 5, v17
	v_or_b32_e32 v32, 4, v20
	v_or_b32_e32 v34, 6, v20
	v_lshlrev_b64 v[20:21], 19, v[20:21]
	v_ashrrev_i32_e32 v23, 31, v22
	v_lshl_add_u64 v[40:41], s[2:3], 0, v[2:3]
	v_lshl_add_u32 v61, v22, 5, v17
	v_lshl_add_u64 v[36:37], v[0:1], 0, v[20:21]
	v_lshlrev_b64 v[38:39], 19, v[22:23]
	global_load_dwordx4 v[6:9], v[40:41], off nt
	global_load_dwordx4 v[20:23], v[40:41], off offset:1024 nt
	global_load_dwordx4 v[24:27], v[40:41], off offset:3072 nt
	global_load_dwordx4 v[28:31], v[40:41], off offset:2048 nt
	s_lshl_b64 s[10:11], s[0:1], 11
	s_add_u32 s2, s38, s10
	s_addc_u32 s3, s39, s11
	v_add_co_u32_e32 v40, vcc, s13, v40
	v_lshl_add_u64 v[42:43], s[2:3], 0, v[4:5]
	s_nop 0
	v_addc_co_u32_e32 v41, vcc, 0, v41, vcc
	v_add_co_u32_e32 v42, vcc, s21, v42
	s_or_b32 s0, s0, 1
	s_nop 0
	v_addc_co_u32_e32 v43, vcc, 0, v43, vcc
	s_mulk_i32 s0, 0x820
	v_lshl_add_u32 v62, v32, 5, v17
	v_lshl_add_u32 v63, v34, 5, v17
	v_ashrrev_i32_e32 v33, 31, v32
	v_ashrrev_i32_e32 v35, 31, v34
	v_lshlrev_b64 v[32:33], 19, v[32:33]
	v_lshlrev_b64 v[34:35], 19, v[34:35]
	v_lshl_add_u64 v[36:37], s[38:39], 0, v[36:37]
	v_lshl_add_u64 v[38:39], v[0:1], 0, v[38:39]
	v_lshl_add_u64 v[32:33], v[0:1], 0, v[32:33]
	v_lshl_add_u64 v[34:35], v[0:1], 0, v[34:35]
	v_lshl_add_u64 v[38:39], s[38:39], 0, v[38:39]
	v_lshl_add_u64 v[32:33], s[38:39], 0, v[32:33]
	v_lshl_add_u64 v[34:35], s[38:39], 0, v[34:35]
	s_add_i32 s5, s5, s12
	v_lshl_add_u64 v[0:1], v[0:1], 0, s[14:15]
	v_lshl_add_u64 v[2:3], v[2:3], 0, s[18:19]
	v_lshl_add_u64 v[4:5], v[4:5], 0, s[16:17]
	s_cmpk_gt_i32 s5, 0x3ff
	s_waitcnt vmcnt(0)
	v_cvt_pk_bf16_f32 v56, v6, v7
	v_pk_mul_f32 v[44:45], v[8:9], v[8:9]
	v_pk_mul_f32 v[46:47], v[6:7], v[6:7]
	s_waitcnt vmcnt(2)
	v_pk_mul_f32 v[48:49], v[22:23], v[22:23]
	v_pk_mul_f32 v[50:51], v[20:21], v[20:21]
	v_pk_mov_b32 v[58:59], v[46:47], v[44:45] op_sel:[1,0]
	v_mov_b32_e32 v47, v45
	v_pk_mov_b32 v[44:45], v[50:51], v[48:49] op_sel:[1,0]
	v_mov_b32_e32 v51, v49
	s_waitcnt vmcnt(1)
	v_mul_f32_e32 v55, v24, v24
	s_waitcnt vmcnt(0)
	v_mul_f32_e32 v52, v29, v29
	v_mul_f32_e32 v54, v31, v31
	v_pk_add_f32 v[46:47], v[58:59], v[46:47]
	v_pk_add_f32 v[44:45], v[44:45], v[50:51]
	v_mul_f32_e32 v67, v25, v25
	v_mul_f32_e32 v68, v26, v26
	v_mul_f32_e32 v69, v27, v27
	v_pk_fma_f32 v[48:49], v[28:29], v[28:29], v[52:53] op_sel_hi:[1,1,0]
	v_pk_fma_f32 v[52:53], v[30:31], v[30:31], v[54:55] op_sel_hi:[1,1,0]
	v_pk_add_f32 v[46:47], v[46:47], v[46:47] op_sel:[0,1] op_sel_hi:[1,0]
	v_pk_add_f32 v[44:45], v[44:45], v[44:45] op_sel:[0,1] op_sel_hi:[1,0]
	v_mov_b32_e32 v49, v68
	v_mov_b32_e32 v53, v69
	v_mov_b32_e32 v47, v55
	v_mov_b32_e32 v45, v67
	v_pk_add_f32 v[48:49], v[48:49], v[52:53]
	v_pk_add_f32 v[44:45], v[46:47], v[44:45]
	v_cvt_pk_bf16_f32 v57, v8, v9
	global_store_dwordx2 v[42:43], v[56:57], off
	v_pk_add_f32 v[44:45], v[44:45], v[48:49]
	s_nop 0
	v_add_f32_e32 v44, v44, v45
	ds_bpermute_b32 v45, v10, v44
	s_waitcnt lgkmcnt(0)
	v_add_f32_e32 v44, v44, v45
	ds_bpermute_b32 v45, v11, v44
	s_waitcnt lgkmcnt(0)
	v_add_f32_e32 v44, v44, v45
	ds_bpermute_b32 v45, v12, v44
	s_waitcnt lgkmcnt(0)
	v_add_f32_e32 v44, v44, v45
	ds_bpermute_b32 v45, v13, v44
	s_waitcnt lgkmcnt(0)
	v_add_f32_e32 v44, v44, v45
	ds_bpermute_b32 v45, v14, v44
	s_waitcnt lgkmcnt(0)
	v_add_f32_e32 v44, v44, v45
	ds_bpermute_b32 v45, v15, v44
	s_waitcnt lgkmcnt(0)
; #define LAS __attribute__((address_space(3)))
; template <bool F32SRC> __device__ __forceinline__ void unorm_chunk(LAS unsigned char* lds, const float* xsrc, bf16_t* hbio, bf16_t* Ug, int chunk, const int tid) {
;     ...
;         if (F32SRC) { const f32x4* xr = (const f32x4*)(xsrc + row * DM) + lane; f32x4 v[4]; float ss = 0.f;
; #pragma unroll
;             for (int j = 0; j < 4; ++j) { v[j] = __builtin_nontemporal_load(xr + 64 * j); ss += (v[j].x * v[j].x + v[j].y * v[j].y) + (v[j].z * v[j].z + v[j].w * v[j].w); }
;             const float rstd = rsqrtf(wsum_l(ss, lane) * (1.0f / DM) + EPS);
;             u32x2* o = (u32x2*)(hbio + row * DM) + lane;
; #pragma unroll
;             for (int j = 0; j < 4; ++j) { u32x2 w; w.x = pg8::cvt_pk_bf16(v[j].x, v[j].y); w.y = pg8::cvt_pk_bf16(v[j].z, v[j].w); o[64 * j] = w;
;                 u32x2 q; q.x = pg8::cvt_pk_bf16(v[j].x * rstd, v[j].y * rstd); q.y = pg8::cvt_pk_bf16(v[j].z * rstd, v[j].w * rstd); *(LAS u32x2*)(T + s * 2080 + (64 * j + lane) * 8) = q; }
;         } else { const u32x4* xr = (const u32x4*)(hbio + row * DM) + lane; u32x4 w[2]; float v[16]; float ss = 0.f;
; #pragma unroll
;             for (int j = 0; j < 2; ++j) { w[j] = xr[64 * j];
;                 v[8 * j + 0] = __uint_as_float(w[j].x << 16); v[8 * j + 1] = __uint_as_float(w[j].x & 0xffff0000u); v[8 * j + 2] = __uint_as_float(w[j].y << 16); v[8 * j + 3] = __uint_as_float(w[j].y & 0xffff0000u);
;                 v[8 * j + 4] = __uint_as_float(w[j].z << 16); v[8 * j + 5] = __uint_as_float(w[j].z & 0xffff0000u); v[8 * j + 6] = __uint_as_float(w[j].w << 16); v[8 * j + 7] = __uint_as_float(w[j].w & 0xffff0000u); }
; #pragma unroll
;             for (int i = 0; i < 16; ++i) ss += v[i] * v[i];
;             const float rstd = rsqrtf(wsum_l(ss, lane) * (1.0f / DM) + EPS);
; #pragma unroll
;             for (int j = 0; j < 2; ++j) { u32x4 q; q.x = pg8::cvt_pk_bf16(v[8 * j] * rstd, v[8 * j + 1] * rstd); q.y = pg8::cvt_pk_bf16(v[8 * j + 2] * rstd, v[8 * j + 3] * rstd);
;                 q.z = pg8::cvt_pk_bf16(v[8 * j + 4] * rstd, v[8 * j + 5] * rstd); q.w = pg8::cvt_pk_bf16(v[8 * j + 6] * rstd, v[8 * j + 7] * rstd); *(LAS u32x4*)(T + s * 2080 + (64 * j + lane) * 16) = q; } }
;     }
;     LDS_WAIT(); __syncthreads();
; #pragma unroll
;     for (int i = 0; i < 4; ++i) { const int gq = 8 * wid + 2 * i + (lane >> 5), l = lane & 31, s = l >> 1, hf = l & 1;
	v_add_f32_e32 v44, v44, v45
	v_fmamk_f32 v44, v44, 0x3a800000, v226
	v_mul_f32_e32 v45, 0x4b800000, v44
	v_cmp_gt_f32_e32 vcc, s24, v44
	s_nop 1
	v_cndmask_b32_e32 v44, v44, v45, vcc
	v_rsq_f32_e32 v44, v44
	s_nop 0
	v_mul_f32_e32 v45, 0x45800000, v44
	v_cndmask_b32_e32 v44, v44, v45, vcc
	v_mul_f32_e32 v6, v6, v44
	v_mul_f32_e32 v7, v7, v44
	v_mul_f32_e32 v8, v8, v44
	v_mul_f32_e32 v9, v9, v44
	v_cvt_pk_bf16_f32 v6, v6, v7
	v_cvt_pk_bf16_f32 v7, v8, v9
	ds_write_b64 v19, v[6:7]
	v_cvt_pk_bf16_f32 v6, v20, v21
	v_cvt_pk_bf16_f32 v7, v22, v23
	v_mul_f32_e32 v45, v20, v44
	v_mul_f32_e32 v46, v21, v44
	v_mul_f32_e32 v47, v22, v44
	v_mul_f32_e32 v48, v23, v44
	global_store_dwordx2 v[42:43], v[6:7], off offset:512
	v_cvt_pk_bf16_f32 v6, v45, v46
	v_cvt_pk_bf16_f32 v7, v47, v48
	ds_write_b64 v19, v[6:7] offset:512
	v_cvt_pk_bf16_f32 v6, v28, v29
	v_cvt_pk_bf16_f32 v7, v30, v31
	v_mul_f32_e32 v49, v28, v44
	v_mul_f32_e32 v50, v29, v44
	v_mul_f32_e32 v51, v30, v44
	v_mul_f32_e32 v52, v31, v44
	global_store_dwordx2 v[42:43], v[6:7], off offset:1024
	v_cvt_pk_bf16_f32 v6, v49, v50
	v_cvt_pk_bf16_f32 v7, v51, v52
	ds_write_b64 v19, v[6:7] offset:1024
	v_cvt_pk_bf16_f32 v6, v24, v25
	v_cvt_pk_bf16_f32 v7, v26, v27
	v_mul_f32_e32 v53, v24, v44
	v_mul_f32_e32 v54, v25, v44
	v_mul_f32_e32 v55, v26, v44
	v_mul_f32_e32 v56, v27, v44
	global_store_dwordx2 v[42:43], v[6:7], off offset:1536
	v_cvt_pk_bf16_f32 v44, v53, v54
	v_cvt_pk_bf16_f32 v45, v55, v56
	global_load_dwordx4 v[6:9], v[40:41], off nt
	global_load_dwordx4 v[20:23], v[40:41], off offset:1024 nt
	global_load_dwordx4 v[24:27], v[40:41], off offset:2048 nt
	global_load_dwordx4 v[28:31], v[40:41], off offset:3072 nt
	ds_write_b64 v19, v[44:45] offset:1536
	v_add_u32_e32 v53, s0, v18
	s_waitcnt vmcnt(3)
	v_cvt_pk_bf16_f32 v54, v6, v7
	v_pk_mul_f32 v[40:41], v[8:9], v[8:9]
	v_pk_mul_f32 v[44:45], v[6:7], v[6:7]
	s_waitcnt vmcnt(2)
	v_pk_mul_f32 v[46:47], v[22:23], v[22:23]
	v_pk_mul_f32 v[48:49], v[20:21], v[20:21]
	v_pk_mov_b32 v[56:57], v[44:45], v[40:41] op_sel:[1,0]
	v_mov_b32_e32 v45, v41
	v_pk_mov_b32 v[40:41], v[48:49], v[46:47] op_sel:[1,0]
	v_mov_b32_e32 v49, v47
	s_waitcnt vmcnt(1)
	v_mul_f32_e32 v50, v25, v25
	v_mul_f32_e32 v52, v27, v27
	v_pk_add_f32 v[44:45], v[56:57], v[44:45]
	v_pk_add_f32 v[40:41], v[40:41], v[48:49]
	s_waitcnt vmcnt(0)
	v_mul_f32_e32 v19, v28, v28
	v_mul_f32_e32 v58, v29, v29
	v_mul_f32_e32 v59, v30, v30
	v_mul_f32_e32 v67, v31, v31
	v_pk_fma_f32 v[46:47], v[24:25], v[24:25], v[50:51] op_sel_hi:[1,1,0]
	v_pk_fma_f32 v[50:51], v[26:27], v[26:27], v[52:53] op_sel_hi:[1,1,0]
	v_pk_add_f32 v[44:45], v[44:45], v[44:45] op_sel:[0,1] op_sel_hi:[1,0]
	v_pk_add_f32 v[40:41], v[40:41], v[40:41] op_sel:[0,1] op_sel_hi:[1,0]
	v_mov_b32_e32 v47, v59
	v_mov_b32_e32 v51, v67
	v_mov_b32_e32 v45, v19
	v_mov_b32_e32 v41, v58
	v_pk_add_f32 v[46:47], v[46:47], v[50:51]
	v_pk_add_f32 v[40:41], v[44:45], v[40:41]
	v_cvt_pk_bf16_f32 v55, v8, v9
	global_store_dwordx2 v[42:43], v[54:55], off offset:2048
	v_pk_add_f32 v[40:41], v[40:41], v[46:47]
	s_nop 0
	v_add_f32_e32 v19, v40, v41
	ds_bpermute_b32 v40, v10, v19
	s_waitcnt lgkmcnt(0)
	v_add_f32_e32 v19, v19, v40
	ds_bpermute_b32 v40, v11, v19
	s_waitcnt lgkmcnt(0)
	v_add_f32_e32 v19, v19, v40
	ds_bpermute_b32 v40, v12, v19
	s_waitcnt lgkmcnt(0)
	v_add_f32_e32 v19, v19, v40
	ds_bpermute_b32 v40, v13, v19
	s_waitcnt lgkmcnt(0)
	v_add_f32_e32 v19, v19, v40
	ds_bpermute_b32 v40, v14, v19
	s_waitcnt lgkmcnt(0)
	v_add_f32_e32 v19, v19, v40
	ds_bpermute_b32 v40, v15, v19
	s_waitcnt lgkmcnt(0)
	v_add_f32_e32 v19, v19, v40
	v_fmamk_f32 v19, v19, 0x3a800000, v226
	v_mul_f32_e32 v40, 0x4b800000, v19
	v_cmp_gt_f32_e32 vcc, s24, v19
	s_nop 1
	v_cndmask_b32_e32 v19, v19, v40, vcc
	v_rsq_f32_e32 v19, v19
	s_nop 0
	v_mul_f32_e32 v40, 0x45800000, v19
	v_cndmask_b32_e32 v19, v19, v40, vcc
	v_mul_f32_e32 v6, v6, v19
	v_mul_f32_e32 v7, v7, v19
	v_mul_f32_e32 v8, v8, v19
	v_mul_f32_e32 v9, v9, v19
	v_cvt_pk_bf16_f32 v6, v6, v7
	v_cvt_pk_bf16_f32 v7, v8, v9
	ds_write_b64 v53, v[6:7]
	v_cvt_pk_bf16_f32 v6, v20, v21
	v_cvt_pk_bf16_f32 v7, v22, v23
	v_mul_f32_e32 v40, v20, v19
	v_mul_f32_e32 v41, v21, v19
	v_mul_f32_e32 v44, v22, v19
	v_mul_f32_e32 v45, v23, v19
	global_store_dwordx2 v[42:43], v[6:7], off offset:2560
	v_cvt_pk_bf16_f32 v6, v40, v41
	v_cvt_pk_bf16_f32 v7, v44, v45
	ds_write_b64 v53, v[6:7] offset:512
	v_cvt_pk_bf16_f32 v6, v24, v25
	v_cvt_pk_bf16_f32 v7, v26, v27
	v_mul_f32_e32 v46, v24, v19
	v_mul_f32_e32 v47, v25, v19
	v_mul_f32_e32 v48, v26, v19
	v_mul_f32_e32 v49, v27, v19
	global_store_dwordx2 v[42:43], v[6:7], off offset:3072
	v_cvt_pk_bf16_f32 v6, v46, v47
	v_cvt_pk_bf16_f32 v7, v48, v49
	ds_write_b64 v53, v[6:7] offset:1024
	v_cvt_pk_bf16_f32 v6, v28, v29
	v_cvt_pk_bf16_f32 v7, v30, v31
	v_mul_f32_e32 v50, v28, v19
	v_mul_f32_e32 v51, v29, v19
	v_mul_f32_e32 v52, v30, v19
	v_mul_f32_e32 v19, v31, v19
	global_store_dwordx2 v[42:43], v[6:7], off offset:3584
	v_cvt_pk_bf16_f32 v6, v50, v51
	v_cvt_pk_bf16_f32 v7, v52, v19
	ds_write_b64 v53, v[6:7] offset:1536
	s_waitcnt lgkmcnt(0)
	s_waitcnt lgkmcnt(0)
	s_barrier
	ds_read_b128 v[6:9], v60
	ds_read_b128 v[20:23], v61
	ds_read_b128 v[24:27], v62
	ds_read_b128 v[28:31], v63
	s_waitcnt lgkmcnt(3)
	global_store_dwordx4 v[36:37], v[6:9], off nt
	s_waitcnt lgkmcnt(2)
	global_store_dwordx4 v[38:39], v[20:23], off nt
	s_waitcnt lgkmcnt(1)
	global_store_dwordx4 v[32:33], v[24:27], off nt
	s_waitcnt lgkmcnt(0)
	global_store_dwordx4 v[34:35], v[28:31], off nt
	s_waitcnt lgkmcnt(0)
	s_barrier
	s_cbranch_scc0 .LBB0_312

; __device__ __forceinline__ unsigned cvt_pk_bf16(float lo, float hi) { unsigned r; asm volatile("v_cvt_pk_bf16_f32 %0, %1, %2" : "=v"(r) : "v"(lo), "v"(hi)); return r; }
; #define LAS __attribute__((address_space(3)))
; #define LDS_WAIT() asm volatile("s_waitcnt lgkmcnt(0)" ::: "memory")
; __device__ __forceinline__ void conv_item(const float* W, int ldw, int K, int c0, int k0, const float* gain, bf16_t* Wt, int n0, LAS float* scr, int lane) {
;     ...
;     for (int i = 0; i < 16; ++i) { const int k = 4 * i + kr; *(LAS f32x4*)(scr + k * 64 + (n4 ^ (((k >> 3) & 7) << 2))) = v[i]; }
;     LDS_WAIT(); asm volatile("" ::: "memory");
;     const int c = lane & 7;
; #pragma unroll
;     for (int j = 0; j < 8; ++j) { const int n = (lane >> 3) + 8 * j; const LAS float* s = scr + (8 * c) * 64 + (n ^ (c << 2));
;         u32x4 o; o.x = pg8::cvt_pk_bf16(s[0 * 64], s[1 * 64]); o.y = pg8::cvt_pk_bf16(s[2 * 64], s[3 * 64]); o.z = pg8::cvt_pk_bf16(s[4 * 64], s[5 * 64]); o.w = pg8::cvt_pk_bf16(s[6 * 64], s[7 * 64]);
;         *(u32x4*)(Wt + (size_t)(n0 + n) * K + k0 + 8 * c) = o; }
;     LDS_WAIT(); asm volatile("" ::: "memory");
.LBB0_324:
	s_waitcnt vmcnt(0)
	ds_write_b128 v86, v[0:3]
	s_waitcnt vmcnt(14)
	ds_write_b128 v86, v[4:7] offset:1024
	s_waitcnt vmcnt(13)
	ds_write_b128 v87, v[8:11] offset:2048
	s_waitcnt vmcnt(12)
	ds_write_b128 v87, v[12:15] offset:3072
	s_waitcnt vmcnt(11)
	ds_write_b128 v88, v[16:19] offset:4096
	s_waitcnt vmcnt(10)
	ds_write_b128 v88, v[20:23] offset:5120
	s_waitcnt vmcnt(9)
	ds_write_b128 v89, v[24:27] offset:6144
	s_waitcnt vmcnt(8)
	ds_write_b128 v89, v[28:31] offset:7168
	s_waitcnt vmcnt(7)
	ds_write_b128 v90, v[32:35] offset:8192
	s_waitcnt vmcnt(6)
	ds_write_b128 v90, v[36:39] offset:9216
	s_waitcnt vmcnt(5)
	ds_write_b128 v91, v[40:43] offset:10240
	s_waitcnt vmcnt(4)
	ds_write_b128 v91, v[44:47] offset:11264
	s_waitcnt vmcnt(3)
	ds_write_b128 v92, v[48:51] offset:12288
	s_waitcnt vmcnt(2)
	ds_write_b128 v92, v[52:55] offset:13312
	s_waitcnt vmcnt(1)
	ds_write_b128 v93, v[56:59] offset:14336
	s_waitcnt vmcnt(0)
	ds_write_b128 v93, v[60:63] offset:15360
	s_waitcnt lgkmcnt(0)
	ds_read2st64_b32 v[0:1], v71 offset1:1
	s_waitcnt lgkmcnt(0)
	v_cvt_pk_bf16_f32 v0, v0, v1
	ds_read2st64_b32 v[2:3], v71 offset0:2 offset1:3
	s_waitcnt lgkmcnt(0)
	v_cvt_pk_bf16_f32 v1, v2, v3
	ds_read2st64_b32 v[2:3], v71 offset0:4 offset1:5
	s_sub_i32 s24, 0, s17
	s_waitcnt lgkmcnt(0)
	v_cvt_pk_bf16_f32 v2, v2, v3
	ds_read2st64_b32 v[4:5], v71 offset0:6 offset1:7
	s_add_i32 s24, s24, s19
	s_waitcnt lgkmcnt(0)
	v_cvt_pk_bf16_f32 v3, v4, v5
	v_add_u32_e32 v4, s24, v65
	s_ashr_i32 s17, s16, 31
	v_ashrrev_i32_e32 v5, 31, v4
	v_lshl_add_u64 v[6:7], s[16:17], 1, v[72:73]
	v_lshlrev_b64 v[10:11], 11, v[4:5]
	v_lshl_add_u64 v[10:11], v[6:7], 0, v[10:11]
	global_store_dwordx4 v[10:11], v[0:3], off nt
	v_add_u32_e32 v10, 8, v4
	v_ashrrev_i32_e32 v11, 31, v10
	ds_read2st64_b32 v[8:9], v94 offset1:1
	s_waitcnt lgkmcnt(0)
	v_cvt_pk_bf16_f32 v0, v8, v9
	ds_read2st64_b32 v[2:3], v94 offset0:2 offset1:3
	v_lshlrev_b64 v[10:11], 11, v[10:11]
	s_waitcnt lgkmcnt(0)
	v_cvt_pk_bf16_f32 v1, v2, v3
	ds_read2st64_b32 v[2:3], v94 offset0:4 offset1:5
	v_lshl_add_u64 v[10:11], v[6:7], 0, v[10:11]
	s_waitcnt lgkmcnt(0)
	v_cvt_pk_bf16_f32 v2, v2, v3
	ds_read2st64_b32 v[8:9], v94 offset0:6 offset1:7
	s_waitcnt lgkmcnt(0)
	v_cvt_pk_bf16_f32 v3, v8, v9
	global_store_dwordx4 v[10:11], v[0:3], off nt
	v_add_u32_e32 v10, 16, v4
	v_ashrrev_i32_e32 v11, 31, v10
	ds_read2st64_b32 v[8:9], v95 offset1:1
	s_waitcnt lgkmcnt(0)
	v_cvt_pk_bf16_f32 v0, v8, v9
	ds_read2st64_b32 v[2:3], v95 offset0:2 offset1:3
	v_lshlrev_b64 v[10:11], 11, v[10:11]
	s_waitcnt lgkmcnt(0)
	v_cvt_pk_bf16_f32 v1, v2, v3
	ds_read2st64_b32 v[2:3], v95 offset0:4 offset1:5
	v_lshl_add_u64 v[10:11], v[6:7], 0, v[10:11]
	s_waitcnt lgkmcnt(0)
	v_cvt_pk_bf16_f32 v2, v2, v3
	ds_read2st64_b32 v[8:9], v95 offset0:6 offset1:7
	s_waitcnt lgkmcnt(0)
	v_cvt_pk_bf16_f32 v3, v8, v9
	global_store_dwordx4 v[10:11], v[0:3], off nt
	v_add_u32_e32 v10, 24, v4
	v_ashrrev_i32_e32 v11, 31, v10
	ds_read2st64_b32 v[8:9], v96 offset1:1
	s_waitcnt lgkmcnt(0)
	v_cvt_pk_bf16_f32 v0, v8, v9
	ds_read2st64_b32 v[2:3], v96 offset0:2 offset1:3
	v_lshlrev_b64 v[10:11], 11, v[10:11]
	s_waitcnt lgkmcnt(0)
	v_cvt_pk_bf16_f32 v1, v2, v3
	ds_read2st64_b32 v[2:3], v96 offset0:4 offset1:5
	v_lshl_add_u64 v[10:11], v[6:7], 0, v[10:11]
	s_waitcnt lgkmcnt(0)
	v_cvt_pk_bf16_f32 v2, v2, v3
	ds_read2st64_b32 v[8:9], v96 offset0:6 offset1:7
	s_waitcnt lgkmcnt(0)
	v_cvt_pk_bf16_f32 v3, v8, v9
	global_store_dwordx4 v[10:11], v[0:3], off nt
	v_add_u32_e32 v10, 32, v4
	v_ashrrev_i32_e32 v11, 31, v10
	ds_read2st64_b32 v[8:9], v97 offset1:1
	s_waitcnt lgkmcnt(0)
	v_cvt_pk_bf16_f32 v0, v8, v9
	ds_read2st64_b32 v[2:3], v97 offset0:2 offset1:3
	v_lshlrev_b64 v[10:11], 11, v[10:11]
	s_waitcnt lgkmcnt(0)
	v_cvt_pk_bf16_f32 v1, v2, v3
	ds_read2st64_b32 v[2:3], v97 offset0:4 offset1:5
	v_lshl_add_u64 v[10:11], v[6:7], 0, v[10:11]
	s_waitcnt lgkmcnt(0)
	v_cvt_pk_bf16_f32 v2, v2, v3
	ds_read2st64_b32 v[8:9], v97 offset0:6 offset1:7
	s_waitcnt lgkmcnt(0)
	v_cvt_pk_bf16_f32 v3, v8, v9
	global_store_dwordx4 v[10:11], v[0:3], off nt
	v_add_u32_e32 v10, 40, v4
	v_ashrrev_i32_e32 v11, 31, v10
	ds_read2st64_b32 v[8:9], v98 offset1:1
	s_waitcnt lgkmcnt(0)
	v_cvt_pk_bf16_f32 v0, v8, v9
	ds_read2st64_b32 v[2:3], v98 offset0:2 offset1:3
	v_lshlrev_b64 v[10:11], 11, v[10:11]
	s_waitcnt lgkmcnt(0)
	v_cvt_pk_bf16_f32 v1, v2, v3
	ds_read2st64_b32 v[2:3], v98 offset0:4 offset1:5
	v_lshl_add_u64 v[10:11], v[6:7], 0, v[10:11]
	s_waitcnt lgkmcnt(0)
	v_cvt_pk_bf16_f32 v2, v2, v3
	ds_read2st64_b32 v[8:9], v98 offset0:6 offset1:7
	s_waitcnt lgkmcnt(0)
	v_cvt_pk_bf16_f32 v3, v8, v9
	global_store_dwordx4 v[10:11], v[0:3], off nt
	v_add_u32_e32 v10, 48, v4
	ds_read2st64_b32 v[8:9], v99 offset1:1
	s_waitcnt lgkmcnt(0)
	v_cvt_pk_bf16_f32 v0, v8, v9
	ds_read2st64_b32 v[2:3], v99 offset0:2 offset1:3
	v_ashrrev_i32_e32 v11, 31, v10
	s_waitcnt lgkmcnt(0)
	v_cvt_pk_bf16_f32 v1, v2, v3
	ds_read2st64_b32 v[2:3], v99 offset0:4 offset1:5
	v_lshlrev_b64 v[10:11], 11, v[10:11]
	v_add_u32_e32 v4, 56, v4
	s_waitcnt lgkmcnt(0)
	v_cvt_pk_bf16_f32 v2, v2, v3
	ds_read2st64_b32 v[8:9], v99 offset0:6 offset1:7
	s_waitcnt lgkmcnt(0)
	v_cvt_pk_bf16_f32 v3, v8, v9
	v_lshl_add_u64 v[10:11], v[6:7], 0, v[10:11]
	v_ashrrev_i32_e32 v5, 31, v4
	ds_read2st64_b32 v[8:9], v100 offset1:1
	global_store_dwordx4 v[10:11], v[0:3], off nt
	v_lshlrev_b64 v[4:5], 11, v[4:5]
	v_lshl_add_u64 v[4:5], v[6:7], 0, v[4:5]
	s_waitcnt lgkmcnt(0)
	v_cvt_pk_bf16_f32 v0, v8, v9
	ds_read2st64_b32 v[2:3], v100 offset0:2 offset1:3
	s_waitcnt lgkmcnt(0)
	v_cvt_pk_bf16_f32 v1, v2, v3
	ds_read2st64_b32 v[2:3], v100 offset0:4 offset1:5
	s_waitcnt lgkmcnt(0)
	v_cvt_pk_bf16_f32 v2, v2, v3
	ds_read2st64_b32 v[8:9], v100 offset0:6 offset1:7
	s_waitcnt lgkmcnt(0)
	v_cvt_pk_bf16_f32 v3, v8, v9
	global_store_dwordx4 v[4:5], v[0:3], off nt
	s_waitcnt lgkmcnt(0)
	v_readlane_b32 s16, v254, 22
	s_add_i32 s18, s18, s16
	s_add_i32 s19, s19, s21
	s_cmpk_lt_i32 s18, 0x100
	v_readlane_b32 s17, v254, 23
	s_cbranch_scc0 .LBB0_327

; #define LAS __attribute__((address_space(3)))
; __device__ __forceinline__ void conv_item(const float* W, int ldw, int K, int c0, int k0, const float* gain, bf16_t* Wt, int n0, LAS float* scr, int lane) {
;     f32x4 v[16];
;     const int kr = lane >> 4, n4 = (lane & 15) * 4;
;     const float* src = W + (size_t)(k0 + kr) * ldw + c0 + n4;
; #pragma unroll
;     for (int i = 0; i < 16; ++i) v[i] = __builtin_nontemporal_load((const f32x4*)(src + (size_t)(4 * i) * ldw));
;     if (gain) {
; #pragma unroll
;         for (int i = 0; i < 16; ++i) v[i] = v[i] * gain[k0 + 4 * i + kr];
;     }
; #pragma unroll
;     for (int i = 0; i < 16; ++i) { const int k = 4 * i + kr; *(LAS f32x4*)(scr + k * 64 + (n4 ^ (((k >> 3) & 7) << 2))) = v[i]; }
.LBB0_329:
	s_ashr_i32 s10, s15, 31
	s_lshr_b32 s10, s10, 28
	s_add_i32 s10, s15, s10
	s_ashr_i32 s10, s10, 4
	s_lshl_b32 s12, s10, 6
	v_or_b32_e32 v0, s12, v76
	s_lshl_b32 s11, s10, 10
	v_ashrrev_i32_e32 v1, 31, v0
	s_sub_i32 s10, s16, s11
	v_lshlrev_b64 v[0:1], 12, v[0:1]
	s_ashr_i32 s11, s10, 31
	v_lshl_add_u64 v[0:1], s[2:3], 0, v[0:1]
	v_lshl_add_u64 v[0:1], s[10:11], 2, v[0:1]
	v_lshl_add_u64 v[0:1], v[0:1], 0, v[208:209]
	v_add_co_u32_e32 v6, vcc, s19, v0
	s_ashr_i32 s13, s12, 31
	s_nop 0
	v_addc_co_u32_e32 v7, vcc, 0, v1, vcc
	v_add_co_u32_e32 v8, vcc, s20, v0
	s_add_i32 s15, s15, s18
	s_nop 0
	v_addc_co_u32_e32 v9, vcc, 0, v1, vcc
	v_add_co_u32_e32 v34, vcc, s21, v0
	s_add_i32 s16, s16, s17
	s_nop 0
	v_addc_co_u32_e32 v35, vcc, 0, v1, vcc
	v_add_co_u32_e32 v38, vcc, s24, v0
	s_cmpk_lt_i32 s15, 0x100
	s_nop 0
	v_addc_co_u32_e32 v39, vcc, 0, v1, vcc
	v_add_co_u32_e32 v42, vcc, s25, v0
	s_nop 1
	v_addc_co_u32_e32 v43, vcc, 0, v1, vcc
	v_add_co_u32_e32 v46, vcc, s26, v0
	s_nop 1
	v_addc_co_u32_e32 v47, vcc, 0, v1, vcc
	v_add_co_u32_e32 v50, vcc, s27, v0
	s_nop 1
	v_addc_co_u32_e32 v51, vcc, 0, v1, vcc
	v_add_co_u32_e32 v54, vcc, s28, v0
	s_nop 1
	v_addc_co_u32_e32 v55, vcc, 0, v1, vcc
	v_add_co_u32_e32 v58, vcc, s29, v0
	s_nop 1
	v_addc_co_u32_e32 v59, vcc, 0, v1, vcc
	v_add_co_u32_e32 v62, vcc, s30, v0
	s_nop 1
	v_addc_co_u32_e32 v63, vcc, 0, v1, vcc
	v_add_co_u32_e32 v86, vcc, s31, v0
	s_nop 1
	v_addc_co_u32_e32 v87, vcc, 0, v1, vcc
	v_add_co_u32_e32 v90, vcc, s35, v0
	s_nop 1
	v_addc_co_u32_e32 v91, vcc, 0, v1, vcc
	v_add_co_u32_e32 v94, vcc, s36, v0
	s_nop 1
	v_addc_co_u32_e32 v95, vcc, 0, v1, vcc
	v_add_co_u32_e32 v98, vcc, s37, v0
	s_nop 1
	v_addc_co_u32_e32 v99, vcc, 0, v1, vcc
	v_add_co_u32_e32 v102, vcc, s38, v0
	s_nop 1
	v_addc_co_u32_e32 v103, vcc, 0, v1, vcc
	global_load_dwordx4 v[0:3], v[0:1], off nt
	s_nop 0
	global_load_dwordx4 v[26:29], v[6:7], off nt
	global_load_dwordx4 v[30:33], v[8:9], off nt
	s_nop 0
	global_load_dwordx4 v[34:37], v[34:35], off nt
	s_nop 0
	global_load_dwordx4 v[38:41], v[38:39], off nt
	s_nop 0
	global_load_dwordx4 v[42:45], v[42:43], off nt
	s_nop 0
	global_load_dwordx4 v[46:49], v[46:47], off nt
	s_nop 0
	global_load_dwordx4 v[50:53], v[50:51], off nt
	s_nop 0
	global_load_dwordx4 v[54:57], v[54:55], off nt
	s_nop 0
	global_load_dwordx4 v[58:61], v[58:59], off nt
	s_nop 0
	global_load_dwordx4 v[72:75], v[62:63], off nt
	s_nop 0
	global_load_dwordx4 v[86:89], v[86:87], off nt
	s_nop 0
	global_load_dwordx4 v[90:93], v[90:91], off nt
	s_nop 0
	global_load_dwordx4 v[94:97], v[94:95], off nt
	s_nop 0
	global_load_dwordx4 v[98:101], v[98:99], off nt
	s_nop 0
	global_load_dwordx4 v[102:105], v[102:103], off nt
	v_add_u32_e32 v8, s10, v65
	v_ashrrev_i32_e32 v9, 31, v8
	v_lshl_add_u64 v[6:7], s[12:13], 1, v[4:5]
	v_lshlrev_b64 v[116:117], 11, v[8:9]
	v_add_u32_e32 v62, 8, v8
	v_lshl_add_u64 v[116:117], v[6:7], 0, v[116:117]
	v_ashrrev_i32_e32 v63, 31, v62
	v_lshlrev_b64 v[62:63], 11, v[62:63]
	v_add_u32_e32 v106, 16, v8
	v_lshl_add_u64 v[62:63], v[6:7], 0, v[62:63]
	v_ashrrev_i32_e32 v107, 31, v106
	v_lshlrev_b64 v[106:107], 11, v[106:107]
	v_add_u32_e32 v108, 24, v8
	v_lshl_add_u64 v[106:107], v[6:7], 0, v[106:107]
	v_ashrrev_i32_e32 v109, 31, v108
	v_lshlrev_b64 v[108:109], 11, v[108:109]
	v_add_u32_e32 v110, 32, v8
	v_lshl_add_u64 v[108:109], v[6:7], 0, v[108:109]
	v_ashrrev_i32_e32 v111, 31, v110
	v_lshlrev_b64 v[110:111], 11, v[110:111]
	v_add_u32_e32 v112, 40, v8
	v_lshl_add_u64 v[110:111], v[6:7], 0, v[110:111]
	v_ashrrev_i32_e32 v113, 31, v112
	v_lshlrev_b64 v[112:113], 11, v[112:113]
	v_add_u32_e32 v114, 48, v8
	v_lshl_add_u64 v[112:113], v[6:7], 0, v[112:113]
	v_ashrrev_i32_e32 v115, 31, v114
	v_lshlrev_b64 v[114:115], 11, v[114:115]
	v_add_u32_e32 v8, 56, v8
	v_lshl_add_u64 v[114:115], v[6:7], 0, v[114:115]
	v_ashrrev_i32_e32 v9, 31, v8
	s_waitcnt vmcnt(0)
	ds_write_b128 v10, v[0:3]
	s_waitcnt vmcnt(14)
	ds_write_b128 v10, v[26:29] offset:1024
	s_waitcnt vmcnt(13)
	ds_write_b128 v11, v[30:33] offset:2048
	s_waitcnt vmcnt(12)
	ds_write_b128 v11, v[34:37] offset:3072
	s_waitcnt vmcnt(11)
	ds_write_b128 v12, v[38:41] offset:4096
	s_waitcnt vmcnt(10)
	ds_write_b128 v12, v[42:45] offset:5120
	s_waitcnt vmcnt(9)
	ds_write_b128 v13, v[46:49] offset:6144
	s_waitcnt vmcnt(8)
	ds_write_b128 v13, v[50:53] offset:7168
	s_waitcnt vmcnt(7)
; __device__ __forceinline__ unsigned cvt_pk_bf16(float lo, float hi) { unsigned r; asm volatile("v_cvt_pk_bf16_f32 %0, %1, %2" : "=v"(r) : "v"(lo), "v"(hi)); return r; }
; #define LAS __attribute__((address_space(3)))
; #define LDS_WAIT() asm volatile("s_waitcnt lgkmcnt(0)" ::: "memory")
; __device__ __forceinline__ void conv_item(const float* W, int ldw, int K, int c0, int k0, const float* gain, bf16_t* Wt, int n0, LAS float* scr, int lane) {
;     ...
;     for (int i = 0; i < 16; ++i) { const int k = 4 * i + kr; *(LAS f32x4*)(scr + k * 64 + (n4 ^ (((k >> 3) & 7) << 2))) = v[i]; }
;     LDS_WAIT(); asm volatile("" ::: "memory");
;     const int c = lane & 7;
; #pragma unroll
;     for (int j = 0; j < 8; ++j) { const int n = (lane >> 3) + 8 * j; const LAS float* s = scr + (8 * c) * 64 + (n ^ (c << 2));
;         u32x4 o; o.x = pg8::cvt_pk_bf16(s[0 * 64], s[1 * 64]); o.y = pg8::cvt_pk_bf16(s[2 * 64], s[3 * 64]); o.z = pg8::cvt_pk_bf16(s[4 * 64], s[5 * 64]); o.w = pg8::cvt_pk_bf16(s[6 * 64], s[7 * 64]);
;         *(u32x4*)(Wt + (size_t)(n0 + n) * K + k0 + 8 * c) = o; }
;     LDS_WAIT(); asm volatile("" ::: "memory");
	ds_write_b128 v14, v[54:57] offset:8192
	s_waitcnt vmcnt(6)
	ds_write_b128 v14, v[58:61] offset:9216
	s_waitcnt vmcnt(5)
	ds_write_b128 v15, v[72:75] offset:10240
	s_waitcnt vmcnt(4)
	ds_write_b128 v15, v[86:89] offset:11264
	s_waitcnt vmcnt(3)
	ds_write_b128 v16, v[90:93] offset:12288
	s_waitcnt vmcnt(2)
	ds_write_b128 v16, v[94:97] offset:13312
	s_waitcnt vmcnt(1)
	ds_write_b128 v17, v[98:101] offset:14336
	s_waitcnt vmcnt(0)
	ds_write_b128 v17, v[102:105] offset:15360
	s_waitcnt lgkmcnt(0)
	ds_read2st64_b32 v[0:1], v18 offset1:1
	s_waitcnt lgkmcnt(0)
	v_cvt_pk_bf16_f32 v0, v0, v1
	ds_read2st64_b32 v[2:3], v18 offset0:2 offset1:3
	s_waitcnt lgkmcnt(0)
	v_cvt_pk_bf16_f32 v1, v2, v3
	ds_read2st64_b32 v[2:3], v18 offset0:4 offset1:5
	s_waitcnt lgkmcnt(0)
	v_cvt_pk_bf16_f32 v2, v2, v3
	ds_read2st64_b32 v[26:27], v18 offset0:6 offset1:7
	s_waitcnt lgkmcnt(0)
	v_cvt_pk_bf16_f32 v3, v26, v27
	ds_read2st64_b32 v[26:27], v19 offset1:1
	global_store_dwordx4 v[116:117], v[0:3], off nt
	v_lshlrev_b64 v[8:9], 11, v[8:9]
	v_lshl_add_u64 v[6:7], v[6:7], 0, v[8:9]
	s_waitcnt lgkmcnt(0)
	v_cvt_pk_bf16_f32 v0, v26, v27
	ds_read2st64_b32 v[2:3], v19 offset0:2 offset1:3
	s_waitcnt lgkmcnt(0)
	v_cvt_pk_bf16_f32 v1, v2, v3
	ds_read2st64_b32 v[2:3], v19 offset0:4 offset1:5
	s_waitcnt lgkmcnt(0)
	v_cvt_pk_bf16_f32 v2, v2, v3
	ds_read2st64_b32 v[26:27], v19 offset0:6 offset1:7
	s_waitcnt lgkmcnt(0)
	v_cvt_pk_bf16_f32 v3, v26, v27
	ds_read2st64_b32 v[26:27], v20 offset1:1
	global_store_dwordx4 v[62:63], v[0:3], off nt
	s_waitcnt lgkmcnt(0)
	s_nop 0
	v_cvt_pk_bf16_f32 v0, v26, v27
	ds_read2st64_b32 v[2:3], v20 offset0:2 offset1:3
	s_waitcnt lgkmcnt(0)
	v_cvt_pk_bf16_f32 v1, v2, v3
	ds_read2st64_b32 v[2:3], v20 offset0:4 offset1:5
	s_waitcnt lgkmcnt(0)
	v_cvt_pk_bf16_f32 v2, v2, v3
	ds_read2st64_b32 v[26:27], v20 offset0:6 offset1:7
	s_waitcnt lgkmcnt(0)
	v_cvt_pk_bf16_f32 v3, v26, v27
	ds_read2st64_b32 v[26:27], v21 offset1:1
	global_store_dwordx4 v[106:107], v[0:3], off nt
	s_waitcnt lgkmcnt(0)
	s_nop 0
	v_cvt_pk_bf16_f32 v0, v26, v27
	ds_read2st64_b32 v[2:3], v21 offset0:2 offset1:3
	s_waitcnt lgkmcnt(0)
	v_cvt_pk_bf16_f32 v1, v2, v3
	ds_read2st64_b32 v[2:3], v21 offset0:4 offset1:5
	s_waitcnt lgkmcnt(0)
	v_cvt_pk_bf16_f32 v2, v2, v3
	ds_read2st64_b32 v[26:27], v21 offset0:6 offset1:7
	s_waitcnt lgkmcnt(0)
	v_cvt_pk_bf16_f32 v3, v26, v27
	ds_read2st64_b32 v[26:27], v22 offset1:1
	global_store_dwordx4 v[108:109], v[0:3], off nt
	s_waitcnt lgkmcnt(0)
	s_nop 0
	v_cvt_pk_bf16_f32 v0, v26, v27
	ds_read2st64_b32 v[2:3], v22 offset0:2 offset1:3
	s_waitcnt lgkmcnt(0)
	v_cvt_pk_bf16_f32 v1, v2, v3
	ds_read2st64_b32 v[2:3], v22 offset0:4 offset1:5
	s_waitcnt lgkmcnt(0)
	v_cvt_pk_bf16_f32 v2, v2, v3
	ds_read2st64_b32 v[26:27], v22 offset0:6 offset1:7
	s_waitcnt lgkmcnt(0)
	v_cvt_pk_bf16_f32 v3, v26, v27
	ds_read2st64_b32 v[26:27], v23 offset1:1
	global_store_dwordx4 v[110:111], v[0:3], off nt
	s_waitcnt lgkmcnt(0)
	s_nop 0
	v_cvt_pk_bf16_f32 v0, v26, v27
	ds_read2st64_b32 v[2:3], v23 offset0:2 offset1:3
	s_waitcnt lgkmcnt(0)
	v_cvt_pk_bf16_f32 v1, v2, v3
	ds_read2st64_b32 v[2:3], v23 offset0:4 offset1:5
	s_waitcnt lgkmcnt(0)
	v_cvt_pk_bf16_f32 v2, v2, v3
	ds_read2st64_b32 v[26:27], v23 offset0:6 offset1:7
	s_waitcnt lgkmcnt(0)
	v_cvt_pk_bf16_f32 v3, v26, v27
	ds_read2st64_b32 v[26:27], v24 offset1:1
	global_store_dwordx4 v[112:113], v[0:3], off nt
	s_waitcnt lgkmcnt(0)
	s_nop 0
	v_cvt_pk_bf16_f32 v0, v26, v27
	ds_read2st64_b32 v[2:3], v24 offset0:2 offset1:3
	s_waitcnt lgkmcnt(0)
	v_cvt_pk_bf16_f32 v1, v2, v3
	ds_read2st64_b32 v[2:3], v24 offset0:4 offset1:5
	s_waitcnt lgkmcnt(0)
	v_cvt_pk_bf16_f32 v2, v2, v3
	ds_read2st64_b32 v[26:27], v24 offset0:6 offset1:7
	s_waitcnt lgkmcnt(0)
	v_cvt_pk_bf16_f32 v3, v26, v27
	ds_read2st64_b32 v[26:27], v25 offset1:1
	global_store_dwordx4 v[114:115], v[0:3], off nt
	s_waitcnt lgkmcnt(0)
	s_nop 0
	v_cvt_pk_bf16_f32 v0, v26, v27
	ds_read2st64_b32 v[2:3], v25 offset0:2 offset1:3
	s_waitcnt lgkmcnt(0)
	v_cvt_pk_bf16_f32 v1, v2, v3
	ds_read2st64_b32 v[2:3], v25 offset0:4 offset1:5
	s_waitcnt lgkmcnt(0)
	v_cvt_pk_bf16_f32 v2, v2, v3
	ds_read2st64_b32 v[26:27], v25 offset0:6 offset1:7
	s_waitcnt lgkmcnt(0)
	v_cvt_pk_bf16_f32 v3, v26, v27
	global_store_dwordx4 v[6:7], v[0:3], off nt
	s_waitcnt lgkmcnt(0)
	s_cbranch_scc1 .LBB0_329
	s_mov_b32 s31, 0x30000
	s_mov_b32 s29, 0x20000
	s_mov_b32 s27, 0x10000
	s_mov_b32 s26, 0x8000

; __device__ __forceinline__ unsigned cvt_pk_bf16(float lo, float hi) { unsigned r; asm volatile("v_cvt_pk_bf16_f32 %0, %1, %2" : "=v"(r) : "v"(lo), "v"(hi)); return r; }
; #define LAS __attribute__((address_space(3)))
; #define LDS_WAIT() asm volatile("s_waitcnt lgkmcnt(0)" ::: "memory")
; __device__ __forceinline__ void conv_item(const float* W, int ldw, int K, int c0, int k0, const float* gain, bf16_t* Wt, int n0, LAS float* scr, int lane) {
;     ...
;     for (int i = 0; i < 16; ++i) { const int k = 4 * i + kr; *(LAS f32x4*)(scr + k * 64 + (n4 ^ (((k >> 3) & 7) << 2))) = v[i]; }
;     LDS_WAIT(); asm volatile("" ::: "memory");
;     const int c = lane & 7;
; #pragma unroll
;     for (int j = 0; j < 8; ++j) { const int n = (lane >> 3) + 8 * j; const LAS float* s = scr + (8 * c) * 64 + (n ^ (c << 2));
;         u32x4 o; o.x = pg8::cvt_pk_bf16(s[0 * 64], s[1 * 64]); o.y = pg8::cvt_pk_bf16(s[2 * 64], s[3 * 64]); o.z = pg8::cvt_pk_bf16(s[4 * 64], s[5 * 64]); o.w = pg8::cvt_pk_bf16(s[6 * 64], s[7 * 64]);
;         *(u32x4*)(Wt + (size_t)(n0 + n) * K + k0 + 8 * c) = o; }
;     LDS_WAIT(); asm volatile("" ::: "memory");
.LBB0_333:
	s_waitcnt vmcnt(0)
	ds_write_b128 v86, v[0:3]
	s_waitcnt vmcnt(14)
	ds_write_b128 v86, v[4:7] offset:1024
	s_waitcnt vmcnt(13)
	ds_write_b128 v87, v[8:11] offset:2048
	s_waitcnt vmcnt(12)
	ds_write_b128 v87, v[12:15] offset:3072
	s_waitcnt vmcnt(11)
	ds_write_b128 v88, v[16:19] offset:4096
	s_waitcnt vmcnt(10)
	ds_write_b128 v88, v[20:23] offset:5120
	s_waitcnt vmcnt(9)
	ds_write_b128 v89, v[24:27] offset:6144
	s_waitcnt vmcnt(8)
	ds_write_b128 v89, v[28:31] offset:7168
	s_waitcnt vmcnt(7)
	ds_write_b128 v90, v[32:35] offset:8192
	s_waitcnt vmcnt(6)
	ds_write_b128 v90, v[36:39] offset:9216
	s_waitcnt vmcnt(5)
	ds_write_b128 v91, v[40:43] offset:10240
	s_waitcnt vmcnt(4)
	ds_write_b128 v91, v[44:47] offset:11264
	s_waitcnt vmcnt(3)
	ds_write_b128 v92, v[48:51] offset:12288
	s_waitcnt vmcnt(2)
	ds_write_b128 v92, v[52:55] offset:13312
	s_waitcnt vmcnt(1)
	ds_write_b128 v93, v[56:59] offset:14336
	s_waitcnt vmcnt(0)
	ds_write_b128 v93, v[60:63] offset:15360
	s_waitcnt lgkmcnt(0)
	ds_read2st64_b32 v[0:1], v71 offset1:1
	s_waitcnt lgkmcnt(0)
	v_cvt_pk_bf16_f32 v0, v0, v1
	ds_read2st64_b32 v[2:3], v71 offset0:2 offset1:3
	s_waitcnt lgkmcnt(0)
	v_cvt_pk_bf16_f32 v1, v2, v3
	ds_read2st64_b32 v[2:3], v71 offset0:4 offset1:5
	s_sub_i32 s19, 0, s15
	s_waitcnt lgkmcnt(0)
	v_cvt_pk_bf16_f32 v2, v2, v3
	ds_read2st64_b32 v[4:5], v71 offset0:6 offset1:7
	s_add_i32 s19, s19, s17
	s_waitcnt lgkmcnt(0)
	v_cvt_pk_bf16_f32 v3, v4, v5
	v_add_u32_e32 v4, s19, v65
	s_ashr_i32 s15, s14, 31
	v_ashrrev_i32_e32 v5, 31, v4
	v_lshl_add_u64 v[6:7], s[14:15], 1, v[72:73]
	v_lshlrev_b64 v[10:11], 11, v[4:5]
	v_lshl_add_u64 v[10:11], v[6:7], 0, v[10:11]
	global_store_dwordx4 v[10:11], v[0:3], off nt
	v_add_u32_e32 v10, 8, v4
	v_ashrrev_i32_e32 v11, 31, v10
	ds_read2st64_b32 v[8:9], v94 offset1:1
	s_waitcnt lgkmcnt(0)
	v_cvt_pk_bf16_f32 v0, v8, v9
	ds_read2st64_b32 v[2:3], v94 offset0:2 offset1:3
	v_lshlrev_b64 v[10:11], 11, v[10:11]
	s_waitcnt lgkmcnt(0)
	v_cvt_pk_bf16_f32 v1, v2, v3
	ds_read2st64_b32 v[2:3], v94 offset0:4 offset1:5
	v_lshl_add_u64 v[10:11], v[6:7], 0, v[10:11]
	s_waitcnt lgkmcnt(0)
	v_cvt_pk_bf16_f32 v2, v2, v3
	ds_read2st64_b32 v[8:9], v94 offset0:6 offset1:7
	s_waitcnt lgkmcnt(0)
	v_cvt_pk_bf16_f32 v3, v8, v9
	global_store_dwordx4 v[10:11], v[0:3], off nt
	v_add_u32_e32 v10, 16, v4
	v_ashrrev_i32_e32 v11, 31, v10
	ds_read2st64_b32 v[8:9], v95 offset1:1
	s_waitcnt lgkmcnt(0)
	v_cvt_pk_bf16_f32 v0, v8, v9
	ds_read2st64_b32 v[2:3], v95 offset0:2 offset1:3
	v_lshlrev_b64 v[10:11], 11, v[10:11]
	s_waitcnt lgkmcnt(0)
	v_cvt_pk_bf16_f32 v1, v2, v3
	ds_read2st64_b32 v[2:3], v95 offset0:4 offset1:5
	v_lshl_add_u64 v[10:11], v[6:7], 0, v[10:11]
	s_waitcnt lgkmcnt(0)
	v_cvt_pk_bf16_f32 v2, v2, v3
	ds_read2st64_b32 v[8:9], v95 offset0:6 offset1:7
	s_waitcnt lgkmcnt(0)
	v_cvt_pk_bf16_f32 v3, v8, v9
	global_store_dwordx4 v[10:11], v[0:3], off nt
	v_add_u32_e32 v10, 24, v4
	v_ashrrev_i32_e32 v11, 31, v10
	ds_read2st64_b32 v[8:9], v96 offset1:1
	s_waitcnt lgkmcnt(0)
	v_cvt_pk_bf16_f32 v0, v8, v9
	ds_read2st64_b32 v[2:3], v96 offset0:2 offset1:3
	v_lshlrev_b64 v[10:11], 11, v[10:11]
	s_waitcnt lgkmcnt(0)
	v_cvt_pk_bf16_f32 v1, v2, v3
	ds_read2st64_b32 v[2:3], v96 offset0:4 offset1:5
	v_lshl_add_u64 v[10:11], v[6:7], 0, v[10:11]
	s_waitcnt lgkmcnt(0)
	v_cvt_pk_bf16_f32 v2, v2, v3
	ds_read2st64_b32 v[8:9], v96 offset0:6 offset1:7
	s_waitcnt lgkmcnt(0)
	v_cvt_pk_bf16_f32 v3, v8, v9
	global_store_dwordx4 v[10:11], v[0:3], off nt
	v_add_u32_e32 v10, 32, v4
	v_ashrrev_i32_e32 v11, 31, v10
	ds_read2st64_b32 v[8:9], v97 offset1:1
	s_waitcnt lgkmcnt(0)
	v_cvt_pk_bf16_f32 v0, v8, v9
	ds_read2st64_b32 v[2:3], v97 offset0:2 offset1:3
	v_lshlrev_b64 v[10:11], 11, v[10:11]
	s_waitcnt lgkmcnt(0)
	v_cvt_pk_bf16_f32 v1, v2, v3
	ds_read2st64_b32 v[2:3], v97 offset0:4 offset1:5
	v_lshl_add_u64 v[10:11], v[6:7], 0, v[10:11]
	s_waitcnt lgkmcnt(0)
	v_cvt_pk_bf16_f32 v2, v2, v3
	ds_read2st64_b32 v[8:9], v97 offset0:6 offset1:7
	s_waitcnt lgkmcnt(0)
	v_cvt_pk_bf16_f32 v3, v8, v9
	global_store_dwordx4 v[10:11], v[0:3], off nt
	v_add_u32_e32 v10, 40, v4
	v_ashrrev_i32_e32 v11, 31, v10
	ds_read2st64_b32 v[8:9], v98 offset1:1
	s_waitcnt lgkmcnt(0)
	v_cvt_pk_bf16_f32 v0, v8, v9
	ds_read2st64_b32 v[2:3], v98 offset0:2 offset1:3
	v_lshlrev_b64 v[10:11], 11, v[10:11]
	s_waitcnt lgkmcnt(0)
	v_cvt_pk_bf16_f32 v1, v2, v3
	ds_read2st64_b32 v[2:3], v98 offset0:4 offset1:5
	v_lshl_add_u64 v[10:11], v[6:7], 0, v[10:11]
	s_waitcnt lgkmcnt(0)
	v_cvt_pk_bf16_f32 v2, v2, v3
	ds_read2st64_b32 v[8:9], v98 offset0:6 offset1:7
	s_waitcnt lgkmcnt(0)
	v_cvt_pk_bf16_f32 v3, v8, v9
	global_store_dwordx4 v[10:11], v[0:3], off nt
	v_add_u32_e32 v10, 48, v4
	ds_read2st64_b32 v[8:9], v99 offset1:1
	s_waitcnt lgkmcnt(0)
	v_cvt_pk_bf16_f32 v0, v8, v9
	ds_read2st64_b32 v[2:3], v99 offset0:2 offset1:3
	v_ashrrev_i32_e32 v11, 31, v10
	s_waitcnt lgkmcnt(0)
	v_cvt_pk_bf16_f32 v1, v2, v3
	ds_read2st64_b32 v[2:3], v99 offset0:4 offset1:5
	v_lshlrev_b64 v[10:11], 11, v[10:11]
	v_add_u32_e32 v4, 56, v4
	s_waitcnt lgkmcnt(0)
	v_cvt_pk_bf16_f32 v2, v2, v3
	ds_read2st64_b32 v[8:9], v99 offset0:6 offset1:7
	s_waitcnt lgkmcnt(0)
	v_cvt_pk_bf16_f32 v3, v8, v9
	v_lshl_add_u64 v[10:11], v[6:7], 0, v[10:11]
	v_ashrrev_i32_e32 v5, 31, v4
	ds_read2st64_b32 v[8:9], v100 offset1:1
	global_store_dwordx4 v[10:11], v[0:3], off nt
	v_lshlrev_b64 v[4:5], 11, v[4:5]
	v_lshl_add_u64 v[4:5], v[6:7], 0, v[4:5]
	s_waitcnt lgkmcnt(0)
	v_cvt_pk_bf16_f32 v0, v8, v9
	ds_read2st64_b32 v[2:3], v100 offset0:2 offset1:3
	s_waitcnt lgkmcnt(0)
	v_cvt_pk_bf16_f32 v1, v2, v3
	ds_read2st64_b32 v[2:3], v100 offset0:4 offset1:5
	s_waitcnt lgkmcnt(0)
	v_cvt_pk_bf16_f32 v2, v2, v3
	ds_read2st64_b32 v[8:9], v100 offset0:6 offset1:7
	s_waitcnt lgkmcnt(0)
	v_cvt_pk_bf16_f32 v3, v8, v9
	global_store_dwordx4 v[4:5], v[0:3], off nt
	s_waitcnt lgkmcnt(0)
	v_readlane_b32 s14, v254, 22
	s_add_i32 s5, s5, s14
	s_add_i32 s17, s17, s18
	s_cmpk_lt_i32 s5, 0x400
	v_readlane_b32 s15, v254, 23
	s_cbranch_scc0 .LBB0_336

; #define LAS __attribute__((address_space(3)))
; __device__ __forceinline__ void conv_item(const float* W, int ldw, int K, int c0, int k0, const float* gain, bf16_t* Wt, int n0, LAS float* scr, int lane) {
;     f32x4 v[16];
;     const int kr = lane >> 4, n4 = (lane & 15) * 4;
;     const float* src = W + (size_t)(k0 + kr) * ldw + c0 + n4;
; #pragma unroll
;     for (int i = 0; i < 16; ++i) v[i] = __builtin_nontemporal_load((const f32x4*)(src + (size_t)(4 * i) * ldw));
;     if (gain) {
; #pragma unroll
;         for (int i = 0; i < 16; ++i) v[i] = v[i] * gain[k0 + 4 * i + kr];
;     }
; #pragma unroll
;     for (int i = 0; i < 16; ++i) { const int k = 4 * i + kr; *(LAS f32x4*)(scr + k * 64 + (n4 ^ (((k >> 3) & 7) << 2))) = v[i]; }
.LBB0_338:
	s_ashr_i32 s2, s12, 31
	s_lshr_b32 s2, s2, 28
	s_add_i32 s2, s12, s2
	s_ashr_i32 s2, s2, 4
	s_lshl_b32 s10, s2, 6
	v_or_b32_e32 v0, s10, v76
	s_lshl_b32 s3, s2, 10
	v_ashrrev_i32_e32 v1, 31, v0
	s_sub_i32 s2, s13, s3
	v_lshlrev_b64 v[0:1], 12, v[0:1]
	s_ashr_i32 s3, s2, 31
	v_lshl_add_u64 v[0:1], s[0:1], 0, v[0:1]
	v_lshl_add_u64 v[0:1], s[2:3], 2, v[0:1]
	v_lshl_add_u64 v[0:1], v[0:1], 0, v[208:209]
	v_add_co_u32_e32 v6, vcc, s15, v0
	s_ashr_i32 s11, s10, 31
	s_nop 0
	v_addc_co_u32_e32 v7, vcc, 0, v1, vcc
	v_add_co_u32_e32 v8, vcc, s17, v0
	s_add_i32 s12, s12, s16
	s_nop 0
	v_addc_co_u32_e32 v9, vcc, 0, v1, vcc
	v_add_co_u32_e32 v34, vcc, s18, v0
	s_add_i32 s13, s13, s14
	s_nop 0
	v_addc_co_u32_e32 v35, vcc, 0, v1, vcc
	v_add_co_u32_e32 v38, vcc, s19, v0
	s_cmpk_lt_i32 s12, 0x400
	s_nop 0
	v_addc_co_u32_e32 v39, vcc, 0, v1, vcc
	v_add_co_u32_e32 v42, vcc, s20, v0
	s_nop 1
	v_addc_co_u32_e32 v43, vcc, 0, v1, vcc
	v_add_co_u32_e32 v46, vcc, s21, v0
	s_nop 1
	v_addc_co_u32_e32 v47, vcc, 0, v1, vcc
	v_add_co_u32_e32 v50, vcc, s24, v0
	s_nop 1
	v_addc_co_u32_e32 v51, vcc, 0, v1, vcc
	v_add_co_u32_e32 v54, vcc, s25, v0
	s_nop 1
	v_addc_co_u32_e32 v55, vcc, 0, v1, vcc
	v_add_co_u32_e32 v58, vcc, s26, v0
	s_nop 1
	v_addc_co_u32_e32 v59, vcc, 0, v1, vcc
	v_add_co_u32_e32 v62, vcc, s27, v0
	s_nop 1
	v_addc_co_u32_e32 v63, vcc, 0, v1, vcc
	v_add_co_u32_e32 v86, vcc, s28, v0
	s_nop 1
	v_addc_co_u32_e32 v87, vcc, 0, v1, vcc
	v_add_co_u32_e32 v90, vcc, s29, v0
	s_nop 1
	v_addc_co_u32_e32 v91, vcc, 0, v1, vcc
	v_add_co_u32_e32 v94, vcc, s30, v0
	s_nop 1
	v_addc_co_u32_e32 v95, vcc, 0, v1, vcc
	v_add_co_u32_e32 v98, vcc, s31, v0
	s_nop 1
	v_addc_co_u32_e32 v99, vcc, 0, v1, vcc
	v_add_co_u32_e32 v102, vcc, s35, v0
	s_nop 1
	v_addc_co_u32_e32 v103, vcc, 0, v1, vcc
	global_load_dwordx4 v[0:3], v[0:1], off nt
	s_nop 0
	global_load_dwordx4 v[26:29], v[6:7], off nt
	global_load_dwordx4 v[30:33], v[8:9], off nt
	s_nop 0
	global_load_dwordx4 v[34:37], v[34:35], off nt
	s_nop 0
	global_load_dwordx4 v[38:41], v[38:39], off nt
	s_nop 0
	global_load_dwordx4 v[42:45], v[42:43], off nt
	s_nop 0
	global_load_dwordx4 v[46:49], v[46:47], off nt
	s_nop 0
	global_load_dwordx4 v[50:53], v[50:51], off nt
	s_nop 0
	global_load_dwordx4 v[54:57], v[54:55], off nt
	s_nop 0
	global_load_dwordx4 v[58:61], v[58:59], off nt
	s_nop 0
	global_load_dwordx4 v[72:75], v[62:63], off nt
	s_nop 0
	global_load_dwordx4 v[86:89], v[86:87], off nt
	s_nop 0
	global_load_dwordx4 v[90:93], v[90:91], off nt
	s_nop 0
	global_load_dwordx4 v[94:97], v[94:95], off nt
	s_nop 0
	global_load_dwordx4 v[98:101], v[98:99], off nt
	s_nop 0
	global_load_dwordx4 v[102:105], v[102:103], off nt
	v_add_u32_e32 v8, s2, v65
	v_ashrrev_i32_e32 v9, 31, v8
	v_lshl_add_u64 v[6:7], s[10:11], 1, v[4:5]
	v_lshlrev_b64 v[116:117], 13, v[8:9]
	v_add_u32_e32 v62, 8, v8
	v_lshl_add_u64 v[116:117], v[6:7], 0, v[116:117]
	v_ashrrev_i32_e32 v63, 31, v62
	v_lshlrev_b64 v[62:63], 13, v[62:63]
	v_add_u32_e32 v106, 16, v8
	v_lshl_add_u64 v[62:63], v[6:7], 0, v[62:63]
	v_ashrrev_i32_e32 v107, 31, v106
	v_lshlrev_b64 v[106:107], 13, v[106:107]
	v_add_u32_e32 v108, 24, v8
	v_lshl_add_u64 v[106:107], v[6:7], 0, v[106:107]
	v_ashrrev_i32_e32 v109, 31, v108
	v_lshlrev_b64 v[108:109], 13, v[108:109]
	v_add_u32_e32 v110, 32, v8
	v_lshl_add_u64 v[108:109], v[6:7], 0, v[108:109]
	v_ashrrev_i32_e32 v111, 31, v110
	v_lshlrev_b64 v[110:111], 13, v[110:111]
	v_add_u32_e32 v112, 40, v8
	v_lshl_add_u64 v[110:111], v[6:7], 0, v[110:111]
	v_ashrrev_i32_e32 v113, 31, v112
	v_lshlrev_b64 v[112:113], 13, v[112:113]
	v_add_u32_e32 v114, 48, v8
	v_lshl_add_u64 v[112:113], v[6:7], 0, v[112:113]
	v_ashrrev_i32_e32 v115, 31, v114
	v_lshlrev_b64 v[114:115], 13, v[114:115]
	v_add_u32_e32 v8, 56, v8
	v_lshl_add_u64 v[114:115], v[6:7], 0, v[114:115]
	v_ashrrev_i32_e32 v9, 31, v8
	s_waitcnt vmcnt(0)
	ds_write_b128 v10, v[0:3]
	s_waitcnt vmcnt(14)
	ds_write_b128 v10, v[26:29] offset:1024
	s_waitcnt vmcnt(13)
	ds_write_b128 v11, v[30:33] offset:2048
	s_waitcnt vmcnt(12)
	ds_write_b128 v11, v[34:37] offset:3072
	s_waitcnt vmcnt(11)
	ds_write_b128 v12, v[38:41] offset:4096
	s_waitcnt vmcnt(10)
	ds_write_b128 v12, v[42:45] offset:5120
	s_waitcnt vmcnt(9)
	ds_write_b128 v13, v[46:49] offset:6144
	s_waitcnt vmcnt(8)
	ds_write_b128 v13, v[50:53] offset:7168
	s_waitcnt vmcnt(7)
; __device__ __forceinline__ unsigned cvt_pk_bf16(float lo, float hi) { unsigned r; asm volatile("v_cvt_pk_bf16_f32 %0, %1, %2" : "=v"(r) : "v"(lo), "v"(hi)); return r; }
; #define LAS __attribute__((address_space(3)))
; #define LDS_WAIT() asm volatile("s_waitcnt lgkmcnt(0)" ::: "memory")
; __device__ __forceinline__ void conv_item(const float* W, int ldw, int K, int c0, int k0, const float* gain, bf16_t* Wt, int n0, LAS float* scr, int lane) {
;     ...
;     for (int i = 0; i < 16; ++i) { const int k = 4 * i + kr; *(LAS f32x4*)(scr + k * 64 + (n4 ^ (((k >> 3) & 7) << 2))) = v[i]; }
;     LDS_WAIT(); asm volatile("" ::: "memory");
;     const int c = lane & 7;
; #pragma unroll
;     for (int j = 0; j < 8; ++j) { const int n = (lane >> 3) + 8 * j; const LAS float* s = scr + (8 * c) * 64 + (n ^ (c << 2));
;         u32x4 o; o.x = pg8::cvt_pk_bf16(s[0 * 64], s[1 * 64]); o.y = pg8::cvt_pk_bf16(s[2 * 64], s[3 * 64]); o.z = pg8::cvt_pk_bf16(s[4 * 64], s[5 * 64]); o.w = pg8::cvt_pk_bf16(s[6 * 64], s[7 * 64]);
;         *(u32x4*)(Wt + (size_t)(n0 + n) * K + k0 + 8 * c) = o; }
;     LDS_WAIT(); asm volatile("" ::: "memory");
	ds_write_b128 v14, v[54:57] offset:8192
	s_waitcnt vmcnt(6)
	ds_write_b128 v14, v[58:61] offset:9216
	s_waitcnt vmcnt(5)
	ds_write_b128 v15, v[72:75] offset:10240
	s_waitcnt vmcnt(4)
	ds_write_b128 v15, v[86:89] offset:11264
	s_waitcnt vmcnt(3)
	ds_write_b128 v16, v[90:93] offset:12288
	s_waitcnt vmcnt(2)
	ds_write_b128 v16, v[94:97] offset:13312
	s_waitcnt vmcnt(1)
	ds_write_b128 v17, v[98:101] offset:14336
	s_waitcnt vmcnt(0)
	ds_write_b128 v17, v[102:105] offset:15360
	s_waitcnt lgkmcnt(0)
	ds_read2st64_b32 v[0:1], v18 offset1:1
	s_waitcnt lgkmcnt(0)
	v_cvt_pk_bf16_f32 v0, v0, v1
	ds_read2st64_b32 v[2:3], v18 offset0:2 offset1:3
	s_waitcnt lgkmcnt(0)
	v_cvt_pk_bf16_f32 v1, v2, v3
	ds_read2st64_b32 v[2:3], v18 offset0:4 offset1:5
	s_waitcnt lgkmcnt(0)
	v_cvt_pk_bf16_f32 v2, v2, v3
	ds_read2st64_b32 v[26:27], v18 offset0:6 offset1:7
	s_waitcnt lgkmcnt(0)
	v_cvt_pk_bf16_f32 v3, v26, v27
	ds_read2st64_b32 v[26:27], v19 offset1:1
	global_store_dwordx4 v[116:117], v[0:3], off nt
	v_lshlrev_b64 v[8:9], 13, v[8:9]
	v_lshl_add_u64 v[6:7], v[6:7], 0, v[8:9]
	s_waitcnt lgkmcnt(0)
	v_cvt_pk_bf16_f32 v0, v26, v27
	ds_read2st64_b32 v[2:3], v19 offset0:2 offset1:3
	s_waitcnt lgkmcnt(0)
	v_cvt_pk_bf16_f32 v1, v2, v3
	ds_read2st64_b32 v[2:3], v19 offset0:4 offset1:5
	s_waitcnt lgkmcnt(0)
	v_cvt_pk_bf16_f32 v2, v2, v3
	ds_read2st64_b32 v[26:27], v19 offset0:6 offset1:7
	s_waitcnt lgkmcnt(0)
	v_cvt_pk_bf16_f32 v3, v26, v27
	ds_read2st64_b32 v[26:27], v20 offset1:1
	global_store_dwordx4 v[62:63], v[0:3], off nt
	s_waitcnt lgkmcnt(0)
	s_nop 0
	v_cvt_pk_bf16_f32 v0, v26, v27
	ds_read2st64_b32 v[2:3], v20 offset0:2 offset1:3
	s_waitcnt lgkmcnt(0)
	v_cvt_pk_bf16_f32 v1, v2, v3
	ds_read2st64_b32 v[2:3], v20 offset0:4 offset1:5
	s_waitcnt lgkmcnt(0)
	v_cvt_pk_bf16_f32 v2, v2, v3
	ds_read2st64_b32 v[26:27], v20 offset0:6 offset1:7
	s_waitcnt lgkmcnt(0)
	v_cvt_pk_bf16_f32 v3, v26, v27
	ds_read2st64_b32 v[26:27], v21 offset1:1
	global_store_dwordx4 v[106:107], v[0:3], off nt
	s_waitcnt lgkmcnt(0)
	s_nop 0
	v_cvt_pk_bf16_f32 v0, v26, v27
	ds_read2st64_b32 v[2:3], v21 offset0:2 offset1:3
	s_waitcnt lgkmcnt(0)
	v_cvt_pk_bf16_f32 v1, v2, v3
	ds_read2st64_b32 v[2:3], v21 offset0:4 offset1:5
	s_waitcnt lgkmcnt(0)
	v_cvt_pk_bf16_f32 v2, v2, v3
	ds_read2st64_b32 v[26:27], v21 offset0:6 offset1:7
	s_waitcnt lgkmcnt(0)
	v_cvt_pk_bf16_f32 v3, v26, v27
	ds_read2st64_b32 v[26:27], v22 offset1:1
	global_store_dwordx4 v[108:109], v[0:3], off nt
	s_waitcnt lgkmcnt(0)
	s_nop 0
	v_cvt_pk_bf16_f32 v0, v26, v27
	ds_read2st64_b32 v[2:3], v22 offset0:2 offset1:3
	s_waitcnt lgkmcnt(0)
	v_cvt_pk_bf16_f32 v1, v2, v3
	ds_read2st64_b32 v[2:3], v22 offset0:4 offset1:5
	s_waitcnt lgkmcnt(0)
	v_cvt_pk_bf16_f32 v2, v2, v3
	ds_read2st64_b32 v[26:27], v22 offset0:6 offset1:7
	s_waitcnt lgkmcnt(0)
	v_cvt_pk_bf16_f32 v3, v26, v27
	ds_read2st64_b32 v[26:27], v23 offset1:1
	global_store_dwordx4 v[110:111], v[0:3], off nt
	s_waitcnt lgkmcnt(0)
	s_nop 0
	v_cvt_pk_bf16_f32 v0, v26, v27
	ds_read2st64_b32 v[2:3], v23 offset0:2 offset1:3
	s_waitcnt lgkmcnt(0)
	v_cvt_pk_bf16_f32 v1, v2, v3
	ds_read2st64_b32 v[2:3], v23 offset0:4 offset1:5
	s_waitcnt lgkmcnt(0)
	v_cvt_pk_bf16_f32 v2, v2, v3
	ds_read2st64_b32 v[26:27], v23 offset0:6 offset1:7
	s_waitcnt lgkmcnt(0)
	v_cvt_pk_bf16_f32 v3, v26, v27
	ds_read2st64_b32 v[26:27], v24 offset1:1
	global_store_dwordx4 v[112:113], v[0:3], off nt
	s_waitcnt lgkmcnt(0)
	s_nop 0
	v_cvt_pk_bf16_f32 v0, v26, v27
	ds_read2st64_b32 v[2:3], v24 offset0:2 offset1:3
	s_waitcnt lgkmcnt(0)
	v_cvt_pk_bf16_f32 v1, v2, v3
	ds_read2st64_b32 v[2:3], v24 offset0:4 offset1:5
	s_waitcnt lgkmcnt(0)
	v_cvt_pk_bf16_f32 v2, v2, v3
	ds_read2st64_b32 v[26:27], v24 offset0:6 offset1:7
	s_waitcnt lgkmcnt(0)
	v_cvt_pk_bf16_f32 v3, v26, v27
	ds_read2st64_b32 v[26:27], v25 offset1:1
	global_store_dwordx4 v[114:115], v[0:3], off nt
	s_waitcnt lgkmcnt(0)
	s_nop 0
	v_cvt_pk_bf16_f32 v0, v26, v27
	ds_read2st64_b32 v[2:3], v25 offset0:2 offset1:3
	s_waitcnt lgkmcnt(0)
	v_cvt_pk_bf16_f32 v1, v2, v3
	ds_read2st64_b32 v[2:3], v25 offset0:4 offset1:5
	s_waitcnt lgkmcnt(0)
	v_cvt_pk_bf16_f32 v2, v2, v3
	ds_read2st64_b32 v[26:27], v25 offset0:6 offset1:7
	s_waitcnt lgkmcnt(0)
	v_cvt_pk_bf16_f32 v3, v26, v27
	global_store_dwordx4 v[6:7], v[0:3], off nt
	s_waitcnt lgkmcnt(0)
	s_cbranch_scc1 .LBB0_338
	s_mov_b32 s27, 0x10000
	s_mov_b32 s26, 0x8000

; __device__ __forceinline__ unsigned cvt_pk_bf16(float lo, float hi) { unsigned r; asm volatile("v_cvt_pk_bf16_f32 %0, %1, %2" : "=v"(r) : "v"(lo), "v"(hi)); return r; }
; #define LAS __attribute__((address_space(3)))
; #define LDS_WAIT() asm volatile("s_waitcnt lgkmcnt(0)" ::: "memory")
; #define INP(i) ((const float*)LDP(i))
; __device__ __forceinline__ void conv_item(const float* W, int ldw, int K, int c0, int k0, const float* gain, bf16_t* Wt, int n0, LAS float* scr, int lane) {
;     ...
;     for (int i = 0; i < 16; ++i) { const int k = 4 * i + kr; *(LAS f32x4*)(scr + k * 64 + (n4 ^ (((k >> 3) & 7) << 2))) = v[i]; }
;     LDS_WAIT(); asm volatile("" ::: "memory");
;     const int c = lane & 7;
; #pragma unroll
;     for (int j = 0; j < 8; ++j) { const int n = (lane >> 3) + 8 * j; const LAS float* s = scr + (8 * c) * 64 + (n ^ (c << 2));
;         u32x4 o; o.x = pg8::cvt_pk_bf16(s[0 * 64], s[1 * 64]); o.y = pg8::cvt_pk_bf16(s[2 * 64], s[3 * 64]); o.z = pg8::cvt_pk_bf16(s[4 * 64], s[5 * 64]); o.w = pg8::cvt_pk_bf16(s[6 * 64], s[7 * 64]);
;         *(u32x4*)(Wt + (size_t)(n0 + n) * K + k0 + 8 * c) = o; }
;     LDS_WAIT(); asm volatile("" ::: "memory");
; __global__ void __launch_bounds__(NWAVES * 64, 2) mk_fwd(Args a) {
;     ...
;                 for (int l = 0; l < DEPTH; ++l)
;                     conv_matrix(INP(21) + (size_t)l * DM * 2048, 2048, DM, 2048, MAP_ID, 0, INP(5) + (size_t)l * DM, (bf16_t*)(BIG + BIG_WKV) + (size_t)l * 2048 * DM, scr, lane, gw, NGW, rot);
.LBB0_345:
	s_waitcnt vmcnt(0)
	ds_write_b128 v74, v[0:3]
	s_waitcnt vmcnt(14)
	ds_write_b128 v74, v[4:7] offset:1024
	s_waitcnt vmcnt(13)
	ds_write_b128 v75, v[8:11] offset:2048
	s_waitcnt vmcnt(12)
	ds_write_b128 v75, v[12:15] offset:3072
	s_waitcnt vmcnt(11)
	ds_write_b128 v79, v[16:19] offset:4096
	s_waitcnt vmcnt(10)
	ds_write_b128 v79, v[20:23] offset:5120
	s_waitcnt vmcnt(9)
	ds_write_b128 v80, v[24:27] offset:6144
	s_waitcnt vmcnt(8)
	ds_write_b128 v80, v[28:31] offset:7168
	s_waitcnt vmcnt(7)
	ds_write_b128 v81, v[32:35] offset:8192
	s_waitcnt vmcnt(6)
	ds_write_b128 v81, v[36:39] offset:9216
	s_waitcnt vmcnt(5)
	ds_write_b128 v82, v[40:43] offset:10240
	s_waitcnt vmcnt(4)
	ds_write_b128 v82, v[44:47] offset:11264
	s_waitcnt vmcnt(3)
	ds_write_b128 v83, v[48:51] offset:12288
	s_waitcnt vmcnt(2)
	ds_write_b128 v83, v[52:55] offset:13312
	s_waitcnt vmcnt(1)
	ds_write_b128 v78, v[56:59] offset:14336
	s_waitcnt vmcnt(0)
	ds_write_b128 v78, v[60:63] offset:15360
	s_waitcnt lgkmcnt(0)
	ds_read2st64_b32 v[0:1], v84 offset1:1
	s_waitcnt lgkmcnt(0)
	v_cvt_pk_bf16_f32 v0, v0, v1
	ds_read2st64_b32 v[2:3], v84 offset0:2 offset1:3
	s_waitcnt lgkmcnt(0)
	v_cvt_pk_bf16_f32 v1, v2, v3
	ds_read2st64_b32 v[2:3], v84 offset0:4 offset1:5
	s_sub_i32 s17, 0, s13
	s_waitcnt lgkmcnt(0)
	v_cvt_pk_bf16_f32 v2, v2, v3
	ds_read2st64_b32 v[4:5], v84 offset0:6 offset1:7
	s_add_i32 s17, s17, s15
	s_waitcnt lgkmcnt(0)
	v_cvt_pk_bf16_f32 v3, v4, v5
	v_add_u32_e32 v4, s17, v65
	s_ashr_i32 s13, s12, 31
	v_ashrrev_i32_e32 v5, 31, v4
	v_lshl_add_u64 v[6:7], s[12:13], 1, v[68:69]
	v_lshlrev_b64 v[10:11], 11, v[4:5]
	v_lshl_add_u64 v[10:11], v[6:7], 0, v[10:11]
	global_store_dwordx4 v[10:11], v[0:3], off nt
	v_add_u32_e32 v10, 8, v4
	v_ashrrev_i32_e32 v11, 31, v10
	ds_read2st64_b32 v[8:9], v85 offset1:1
	s_waitcnt lgkmcnt(0)
	v_cvt_pk_bf16_f32 v0, v8, v9
	ds_read2st64_b32 v[2:3], v85 offset0:2 offset1:3
	v_lshlrev_b64 v[10:11], 11, v[10:11]
	s_waitcnt lgkmcnt(0)
	v_cvt_pk_bf16_f32 v1, v2, v3
	ds_read2st64_b32 v[2:3], v85 offset0:4 offset1:5
	v_lshl_add_u64 v[10:11], v[6:7], 0, v[10:11]
	s_waitcnt lgkmcnt(0)
	v_cvt_pk_bf16_f32 v2, v2, v3
	ds_read2st64_b32 v[8:9], v85 offset0:6 offset1:7
	s_waitcnt lgkmcnt(0)
	v_cvt_pk_bf16_f32 v3, v8, v9
	global_store_dwordx4 v[10:11], v[0:3], off nt
	v_add_u32_e32 v10, 16, v4
	v_ashrrev_i32_e32 v11, 31, v10
	ds_read2st64_b32 v[8:9], v86 offset1:1
	s_waitcnt lgkmcnt(0)
	v_cvt_pk_bf16_f32 v0, v8, v9
	ds_read2st64_b32 v[2:3], v86 offset0:2 offset1:3
	v_lshlrev_b64 v[10:11], 11, v[10:11]
	s_waitcnt lgkmcnt(0)
	v_cvt_pk_bf16_f32 v1, v2, v3
	ds_read2st64_b32 v[2:3], v86 offset0:4 offset1:5
	v_lshl_add_u64 v[10:11], v[6:7], 0, v[10:11]
	s_waitcnt lgkmcnt(0)
	v_cvt_pk_bf16_f32 v2, v2, v3
	ds_read2st64_b32 v[8:9], v86 offset0:6 offset1:7
	s_waitcnt lgkmcnt(0)
	v_cvt_pk_bf16_f32 v3, v8, v9
	global_store_dwordx4 v[10:11], v[0:3], off nt
	v_add_u32_e32 v10, 24, v4
	v_ashrrev_i32_e32 v11, 31, v10
	ds_read2st64_b32 v[8:9], v87 offset1:1
	s_waitcnt lgkmcnt(0)
	v_cvt_pk_bf16_f32 v0, v8, v9
	ds_read2st64_b32 v[2:3], v87 offset0:2 offset1:3
	v_lshlrev_b64 v[10:11], 11, v[10:11]
	s_waitcnt lgkmcnt(0)
	v_cvt_pk_bf16_f32 v1, v2, v3
	ds_read2st64_b32 v[2:3], v87 offset0:4 offset1:5
	v_lshl_add_u64 v[10:11], v[6:7], 0, v[10:11]
	s_waitcnt lgkmcnt(0)
	v_cvt_pk_bf16_f32 v2, v2, v3
	ds_read2st64_b32 v[8:9], v87 offset0:6 offset1:7
	s_waitcnt lgkmcnt(0)
	v_cvt_pk_bf16_f32 v3, v8, v9
	global_store_dwordx4 v[10:11], v[0:3], off nt
	v_add_u32_e32 v10, 32, v4
	v_ashrrev_i32_e32 v11, 31, v10
	ds_read2st64_b32 v[8:9], v88 offset1:1
	s_waitcnt lgkmcnt(0)
	v_cvt_pk_bf16_f32 v0, v8, v9
	ds_read2st64_b32 v[2:3], v88 offset0:2 offset1:3
	v_lshlrev_b64 v[10:11], 11, v[10:11]
	s_waitcnt lgkmcnt(0)
	v_cvt_pk_bf16_f32 v1, v2, v3
	ds_read2st64_b32 v[2:3], v88 offset0:4 offset1:5
	v_lshl_add_u64 v[10:11], v[6:7], 0, v[10:11]
	s_waitcnt lgkmcnt(0)
	v_cvt_pk_bf16_f32 v2, v2, v3
	ds_read2st64_b32 v[8:9], v88 offset0:6 offset1:7
	s_waitcnt lgkmcnt(0)
	v_cvt_pk_bf16_f32 v3, v8, v9
	global_store_dwordx4 v[10:11], v[0:3], off nt
	v_add_u32_e32 v10, 40, v4
	v_ashrrev_i32_e32 v11, 31, v10
	ds_read2st64_b32 v[8:9], v89 offset1:1
	s_waitcnt lgkmcnt(0)
	v_cvt_pk_bf16_f32 v0, v8, v9
	ds_read2st64_b32 v[2:3], v89 offset0:2 offset1:3
	v_lshlrev_b64 v[10:11], 11, v[10:11]
	s_waitcnt lgkmcnt(0)
	v_cvt_pk_bf16_f32 v1, v2, v3
	ds_read2st64_b32 v[2:3], v89 offset0:4 offset1:5
	v_lshl_add_u64 v[10:11], v[6:7], 0, v[10:11]
	s_waitcnt lgkmcnt(0)
	v_cvt_pk_bf16_f32 v2, v2, v3
	ds_read2st64_b32 v[8:9], v89 offset0:6 offset1:7
	s_waitcnt lgkmcnt(0)
	v_cvt_pk_bf16_f32 v3, v8, v9
	global_store_dwordx4 v[10:11], v[0:3], off nt
	v_add_u32_e32 v10, 48, v4
	ds_read2st64_b32 v[8:9], v90 offset1:1
	s_waitcnt lgkmcnt(0)
	v_cvt_pk_bf16_f32 v0, v8, v9
	ds_read2st64_b32 v[2:3], v90 offset0:2 offset1:3
	v_ashrrev_i32_e32 v11, 31, v10
	s_waitcnt lgkmcnt(0)
	v_cvt_pk_bf16_f32 v1, v2, v3
	ds_read2st64_b32 v[2:3], v90 offset0:4 offset1:5
	v_lshlrev_b64 v[10:11], 11, v[10:11]
	v_add_u32_e32 v4, 56, v4
	s_waitcnt lgkmcnt(0)
	v_cvt_pk_bf16_f32 v2, v2, v3
	ds_read2st64_b32 v[8:9], v90 offset0:6 offset1:7
	s_waitcnt lgkmcnt(0)
	v_cvt_pk_bf16_f32 v3, v8, v9
	v_lshl_add_u64 v[10:11], v[6:7], 0, v[10:11]
	v_ashrrev_i32_e32 v5, 31, v4
	ds_read2st64_b32 v[8:9], v77 offset1:1
	global_store_dwordx4 v[10:11], v[0:3], off nt
	v_lshlrev_b64 v[4:5], 11, v[4:5]
	v_lshl_add_u64 v[4:5], v[6:7], 0, v[4:5]
	s_waitcnt lgkmcnt(0)
	v_cvt_pk_bf16_f32 v0, v8, v9
	ds_read2st64_b32 v[2:3], v77 offset0:2 offset1:3
	s_waitcnt lgkmcnt(0)
	v_cvt_pk_bf16_f32 v1, v2, v3
	ds_read2st64_b32 v[2:3], v77 offset0:4 offset1:5
	s_waitcnt lgkmcnt(0)
	v_cvt_pk_bf16_f32 v2, v2, v3
	ds_read2st64_b32 v[8:9], v77 offset0:6 offset1:7
	s_waitcnt lgkmcnt(0)
	v_cvt_pk_bf16_f32 v3, v8, v9
	global_store_dwordx4 v[4:5], v[0:3], off nt
	s_waitcnt lgkmcnt(0)
	v_readlane_b32 s12, v254, 22
	s_add_i32 s14, s14, s12
	s_add_i32 s15, s15, s16
	s_cmpk_lt_i32 s14, 0x200
	v_readlane_b32 s13, v254, 23
	s_cbranch_scc0 .LBB0_342
